# K-tile LDS swizzle widened to 4 bits (conflict-free K fragment reads) + prior: P1 loop, epilogue hoist
# speedup vs baseline: 1.0102x; 1.0009x over previous
; #define LAS __attribute__((address_space(3)))
; #define SBAR() __builtin_amdgcn_sched_barrier(0)
; #define WAITV_BAR(N) asm volatile("s_waitcnt vmcnt(" #N ") lgkmcnt(0)\n\ts_barrier" ::: "memory")
; #define DMA_K(t, slot) do { _Pragma("unroll") for (int i_ = 0; i_ < 2; ++i_) __builtin_amdgcn_global_load_lds((const unsigned*)((const char*)Kh + (size_t)(t) * (KVBLK * D * 2) + dof.k[i_]), \
;         (LAS unsigned*)((LAS unsigned char*)lds3 + OFF_K + (slot) + (wid * 2 + i_) * 1024), 16, 0, 0); } while (0)
; #define DMA_V(t, slot) do { _Pragma("unroll") for (int i_ = 0; i_ < 2; ++i_) __builtin_amdgcn_global_load_lds((const unsigned*)((const char*)Vh + (size_t)(t) * (KVBLK * D * 2) + dof.v[i_]), \
;         (LAS unsigned*)((LAS unsigned char*)lds3 + (slot) + (wid * 2 + i_) * 1024), 16, 0, 0); } while (0)
; __device__ __forceinline__ DmaOff dma_offsets(int wid, int lane) {
;     DmaOff d;
; #pragma unroll
;     for (int i = 0; i < 2; ++i) { const int pc = wid * 2 + i, q = pc * 64 + lane;
;         const int row = q >> 4, j = (q & 15) ^ (row & 7); d.k[i] = (unsigned)(row * 256 + j * 16);
;         const int s = q >> 5, w = q & 31, kk = (s >> 2) * 8 + (w >> 2), c = (s & 3) * 32 + (w & 3) * 8, k = (kk & ~0xC) | ((kk & 4) << 1) | ((kk & 8) >> 1);
;         d.v[i] = (unsigned)(k * 256 + c * 2); }
;     return d;
; }
; __device__ __forceinline__ void fox_prime(const BlockRef& cur, char* lds, Seam& S, const int tid) {
;     const int wid = __builtin_amdgcn_readfirstlane(tid >> 6), lane = tid & 63, r32 = lane & 31, hi = lane >> 5;
;     LAS unsigned char* lds3 = (LAS unsigned char*)lds; const DmaOff dof = dma_offsets(wid, lane);
;     const bf16_t* Kh = cur.K; const bf16_t* Vh = cur.V;
; #pragma unroll
;     for (int d0 = 0; d0 < 8; ++d0) S.qr[d0] = load8(cur.Q + (size_t)(wid * QBLK + r32) * LD + d0 * 16 + hi * 8);
;     SBAR(); DMA_K(0, 0); DMA_K(1, SLOT); DMA_V(0, 0); SBAR();
;     WAITV_BAR(0);
.LBB0_520:
	s_or_b64 exec, exec, s[2:3]
	s_lshl_b32 s2, s60, 8
	v_writelane_b32 v247, s60, 11
	s_and_b32 s2, s2, 0x700
	s_and_b32 s3, s4, 15
	s_lshl_b32 s5, s11, 12
	v_writelane_b32 v247, s2, 12
	s_xor_b32 s4, s2, 0xf00
	v_writelane_b32 v247, s5, 13
	s_or_b32 s6, s4, s5
	v_readlane_b32 s12, v248, 63
	s_ashr_i32 s7, s6, 31
	v_readlane_b32 s13, v247, 0
	s_lshl_b64 s[6:7], s[6:7], 11
	s_mov_b32 s11, s13
	s_lshl_b32 s10, s10, 7
	v_writelane_b32 v248, s10, 63
	s_or_b32 s6, s6, s10
	s_lshl_b64 s[78:79], s[6:7], 1
	s_add_u32 s6, s93, s78
	v_readlane_b32 s2, v248, 37
	s_addc_u32 s7, s2, s79
	s_mul_hi_i32 s2, s9, 0x104000
	s_mul_i32 s9, s9, 0x104000
	v_readlane_b32 s5, v248, 38
	s_add_u32 s30, s5, s9
	v_readlane_b32 s5, v248, 39
	s_addc_u32 s31, s5, s2
	v_readlane_b32 s5, v248, 40
	v_writelane_b32 v247, s11, 0
	s_add_u32 s10, s5, s9
	v_readlane_b32 s5, v248, 41
	s_addc_u32 s11, s5, s2
	v_readfirstlane_b32 s2, v155
	s_ashr_i32 s9, s2, 6
	v_and_b32_e32 v199, 31, v155
	s_lshl_b32 s14, s9, 5
	v_or_b32_e32 v0, s14, v199
	v_ashrrev_i32_e32 v1, 31, v0
	v_lshlrev_b64 v[132:133], 12, v[0:1]
	v_lshrrev_b32_e32 v2, 1, v155
	v_lshl_add_u64 v[0:1], s[6:7], 0, v[132:133]
	v_and_b32_e32 v128, 16, v2
	v_lshl_add_u64 v[0:1], v[0:1], 0, v[128:129]
	s_waitcnt lgkmcnt(0)
	s_barrier
	global_load_dwordx4 v[96:99], v[0:1], off
	global_load_dwordx4 v[100:103], v[0:1], off offset:32
	global_load_dwordx4 v[104:107], v[0:1], off offset:64
	global_load_dwordx4 v[108:111], v[0:1], off offset:96
	global_load_dwordx4 v[112:115], v[0:1], off offset:128
	global_load_dwordx4 v[116:119], v[0:1], off offset:160
	global_load_dwordx4 v[120:123], v[0:1], off offset:192
	global_load_dwordx4 v[124:127], v[0:1], off offset:224
	s_lshl_b32 s5, s9, 7
	v_or_b32_e32 v1, s5, v198
	s_ashr_i32 s5, s5, 4
	v_lshrrev_b32_e32 v191, 2, v198
	v_bitop3_b32 v16, s5, -13, v191 bitop3:0xc8
	v_lshrrev_b32_e32 v0, 1, v198
	s_lshr_b32 s5, s5, 1
	v_and_b32_e32 v200, 8, v0
	s_and_b32 s5, s5, 4
	v_or3_b32 v0, v16, s5, v200
	v_and_b32_e32 v203, 15, v155
	v_lshlrev_b32_e32 v4, 3, v198
	v_lshlrev_b32_e32 v2, 8, v0
	v_ashrrev_i32_e32 v0, 4, v1
	v_and_b32_e32 v202, 24, v4
	v_bitop3_b32 v3, v0, v203, 15 bitop3:0x6c
	v_lshlrev_b32_e32 v0, 8, v0
	v_or_b32_e32 v1, 64, v1
	v_lshl_or_b32 v5, v3, 4, v0
	v_and_or_b32 v0, v155, 32, v202
	v_ashrrev_i32_e32 v3, 4, v1
	s_movk_i32 s6, 0x60
	v_lshlrev_b32_e32 v204, 1, v0
	v_bitop3_b32 v6, v3, v203, 15 bitop3:0x6c
	v_lshlrev_b32_e32 v3, 8, v3
	v_and_or_b32 v1, v1, s6, v202
	s_mov_b32 s71, 4
	v_or_b32_e32 v0, v2, v204
	v_lshl_or_b32 v148, v6, 4, v3
	v_lshl_or_b32 v2, v1, 1, v2
	s_or_b32 s7, s4, 64
	s_lshl_b32 s6, s9, 11
	s_add_i32 s70, s6, 0
	v_writelane_b32 v247, s9, 14
	s_add_i32 s6, s70, 0xc000
	v_writelane_b32 v247, s6, 15
	s_mov_b32 m0, s6
	s_add_i32 s6, s70, 0xc400
	s_add_u32 s12, s30, 0x4000
	global_load_lds_dwordx4 v5, s[30:31]
	v_writelane_b32 v247, s6, 16
	s_mov_b32 m0, s6
	s_addc_u32 s13, s31, 0
	s_add_i32 s6, s70, 0x10000
	global_load_lds_dwordx4 v148, s[30:31]
	v_writelane_b32 v247, s6, 17
	s_mov_b32 m0, s6
	s_add_i32 s6, s70, 0x10400
	global_load_lds_dwordx4 v5, s[12:13]
	s_mov_b32 m0, s6
	v_writelane_b32 v247, s6, 18
	global_load_lds_dwordx4 v148, s[12:13]
	s_mov_b32 m0, s70
	s_add_i32 s6, s70, 0x400
	global_load_lds_dwordx4 v0, s[10:11]
	s_mov_b32 m0, s6
	v_writelane_b32 v247, s6, 19
	global_load_lds_dwordx4 v2, s[10:11]
	v_mov_b32_e32 v128, v5
	v_mov_b32_e32 v149, v129
	v_mov_b32_e32 v1, v129
	v_mov_b32_e32 v3, v129
	v_lshl_add_u64 v[144:145], s[30:31], 0, v[128:129]
	v_lshl_add_u64 v[142:143], s[30:31], 0, v[148:149]
	v_lshl_add_u64 v[136:137], s[12:13], 0, v[128:129]
	v_writelane_b32 v247, s12, 20
	v_lshl_add_u64 v[140:141], s[10:11], 0, v[0:1]
	v_lshl_add_u64 v[134:135], s[10:11], 0, v[2:3]
	v_lshl_add_u64 v[138:139], s[12:13], 0, v[148:149]
	v_writelane_b32 v247, s13, 21
	v_lshlrev_b32_e32 v17, 1, v198
	s_waitcnt vmcnt(0) lgkmcnt(0)
	s_barrier
	s_and_b32 s2, s2, 0x3fffffc0
	v_lshlrev_b32_e32 v1, 4, v198
	v_and_b32_e32 v3, 32, v17
	s_movk_i32 s16, 0xc0
	v_lshrrev_b32_e32 v213, 5, v198
	s_lshl_b32 s2, s2, 2
	v_and_or_b32 v1, v1, s16, v3
	v_and_b32_e32 v3, 0x100, v4
	s_lshr_b32 s93, s7, 6
	v_lshlrev_b32_e32 v201, 2, v213
	s_add_i32 s6, s2, 0
	v_or3_b32 v1, v1, v3, v202
	s_add_i32 s6, s6, 0x18000
	s_add_u32 s66, s30, 0x8000
	s_addc_u32 s67, s31, 0
	s_add_i32 m0, s70, 0x14000
	s_add_i32 s91, s14, s7
	global_load_lds_dwordx4 v5, s[66:67]
	s_add_i32 m0, s70, 0x14400
	s_add_u32 s12, s10, 0x4000
	global_load_lds_dwordx4 v148, s[66:67]
	v_writelane_b32 v247, s10, 22
	s_addc_u32 s13, s11, 0
	s_add_i32 m0, s70, 0x4000
	v_writelane_b32 v247, s11, 23
	global_load_lds_dwordx4 v0, s[12:13]
	s_add_i32 m0, s70, 0x4400
	v_writelane_b32 v247, s12, 24
	s_add_i32 s93, s93, 4
	s_cmp_lg_u32 0, -1
	s_cselect_b32 s7, 0, 0
	s_movk_i32 s73, 0x4000
	s_mov_b32 s2, 0
	global_load_lds_dwordx4 v2, s[12:13]
	v_add_u32_e32 v192, s7, v1
	v_writelane_b32 v247, s13, 25
	v_lshlrev_b32_e32 v146, 4, v213
	v_lshlrev_b32_e32 v22, 4, v155
	v_lshlrev_b32_e32 v18, 8, v199
	v_and_b32_e32 v19, 0xf0, v22
	v_or_b32_e32 v20, 32, v146
	v_readlane_b32 s7, v247, 2
	v_bitop3_b32 v193, v146, v18, v19 bitop3:0xde
	v_bitop3_b32 v194, v20, v18, v19 bitop3:0xde
	v_or_b32_e32 v20, 64, v146
	v_add_u32_e32 v205, s7, v146
	v_add_u32_e32 v209, 0, v193
	v_bitop3_b32 v195, v20, v18, v19 bitop3:0xde
	v_or_b32_e32 v20, 0x60, v146
	ds_read_b128 v[0:3], v205 offset:128
	ds_read_b128 v[4:7], v205 offset:160
	ds_read_b128 v[8:11], v205 offset:192
	ds_read_b128 v[12:15], v205 offset:224
	v_bitop3_b32 v196, v20, v18, v19 bitop3:0xde
	ds_read_b128 v[18:21], v209 offset:57344
	v_add_u32_e32 v208, 0, v194
	s_waitcnt vmcnt(0) lgkmcnt(0)
; #define LAS __attribute__((address_space(3)))
; __device__ __forceinline__ void partialSM(f32x16& p0, f32x16& p1, float& m_reg, float& mn, float& alpha) {
;     float pmax = p0[0];
; #pragma unroll
;     for (int r = 1; r < 16; ++r) pmax = fmaxf(pmax, p0[r]);
; #pragma unroll
;     for (int r = 0; r < 16; ++r) pmax = fmaxf(pmax, p1[r]);
;     { auto rr = __builtin_amdgcn_permlane32_swap(__float_as_uint(pmax), __float_as_uint(pmax), false, false);
;       pmax = fmaxf(__uint_as_float(rr[0]), __uint_as_float(rr[1])); }
;     if (__builtin_expect(__all((pmax - m_reg) <= THR2), 1)) { mn = m_reg; alpha = 1.f; }
;     else { mn = fmaxf(m_reg, pmax); alpha = __builtin_amdgcn_exp2f(m_reg - mn); m_reg = mn; }
; #pragma unroll
;     for (int r = 0; r < 16; ++r) p0[r] = p0[r] - mn;
; #pragma unroll
;     for (int r = 0; r < 16; ++r) p1[r] = p1[r] - mn;
; #pragma unroll
;     for (int r = 0; r < 16; ++r) p0[r] = __builtin_amdgcn_exp2f(p0[r]);
; }
; __device__ __forceinline__ void qkt(f32x16& p0, f32x16& p1, const char* Kslot, int r32, int hi, const bf16x8* qr, const LAS f32x4* cp) {
; #pragma unroll
;     for (int g = 0; g < 4; ++g) { const f32x4 c0 = cp[2 * g], c1 = cp[8 + 2 * g];
; #pragma unroll
;         for (int j = 0; j < 4; ++j) { p0[4 * g + j] = c0[j]; p1[4 * g + j] = c1[j]; } }
;     const char* kb[4];
; #pragma unroll
;     for (int dd = 0; dd < 4; ++dd) kb[dd] = Kslot + KSWZ(r32, (dd * 16 + hi * 8) * 2);
; #pragma unroll
;     for (int d0 = 0; d0 < 8; ++d0) { const char* a = kb[d0 & 3] + (d0 >> 2) * 128;
;         bf16x8 b0 = *reinterpret_cast<const bf16x8*>(a);
;         bf16x8 b1 = *reinterpret_cast<const bf16x8*>(a + 32 * 256);
;         p0 = __builtin_amdgcn_mfma_f32_32x32x16_bf16(b0, qr[d0], p0, 0, 0, 0);
;         p1 = __builtin_amdgcn_mfma_f32_32x32x16_bf16(b1, qr[d0], p1, 0, 0, 0); }
; }
	v_mfma_f32_32x32x16_bf16 v[0:15], v[18:21], v[96:99], v[0:15]
	ds_read_b128 v[18:21], v208 offset:57344
	v_add_u32_e32 v207, 0, v195
	v_add_u32_e32 v206, 0, v196
	s_mov_b32 s7, 0xff800000
	s_waitcnt lgkmcnt(0)
	v_mfma_f32_32x32x16_bf16 v[0:15], v[18:21], v[100:103], v[0:15]
	ds_read_b128 v[18:21], v207 offset:57344
	s_waitcnt lgkmcnt(0)
	v_mfma_f32_32x32x16_bf16 v[0:15], v[18:21], v[104:107], v[0:15]
	ds_read_b128 v[18:21], v206 offset:57344
	s_waitcnt lgkmcnt(0)
	v_mfma_f32_32x32x16_bf16 v[0:15], v[18:21], v[108:111], v[0:15]
	v_xor_b32_e32 v249, 0x80, v209
	v_xor_b32_e32 v250, 0x80, v208
	v_xor_b32_e32 v251, 0x80, v207
	v_xor_b32_e32 v252, 0x80, v206
	ds_read_b128 v[18:21], v249 offset:57344
	s_waitcnt lgkmcnt(0)
	v_mfma_f32_32x32x16_bf16 v[0:15], v[18:21], v[112:115], v[0:15]
	ds_read_b128 v[18:21], v250 offset:57344
	s_waitcnt lgkmcnt(0)
	v_mfma_f32_32x32x16_bf16 v[0:15], v[18:21], v[116:119], v[0:15]
	ds_read_b128 v[18:21], v251 offset:57344
	s_waitcnt lgkmcnt(0)
	v_mfma_f32_32x32x16_bf16 v[0:15], v[18:21], v[120:123], v[0:15]
	ds_read_b128 v[18:21], v252 offset:57344
	s_waitcnt lgkmcnt(0)
	v_mfma_f32_32x32x16_bf16 v[0:15], v[18:21], v[124:127], v[0:15]
	s_nop 11
	v_max3_f32 v0, v8, s7, v9
	v_max3_f32 v0, v0, v10, v11
	v_max3_f32 v0, v0, v12, v13
	v_max3_f32 v0, v0, v14, v15
	v_mov_b32_e32 v1, v0
	s_nop 1
	v_permlane32_swap_b32_e32 v0, v1
	v_max_f32_e32 v1, v1, v1
	v_max_f32_e32 v0, v0, v0
	v_max_f32_e32 v0, v0, v1
	v_add_f32_e32 v1, 0x7149f2ca, v0
	v_cmp_ge_f32_e32 vcc, s33, v1
	v_max_f32_e32 v0, 0xf149f2ca, v0
	s_cmp_eq_u64 vcc, exec
	v_sub_f32_e32 v1, 0xf149f2ca, v0
	s_cselect_b64 vcc, -1, 0
	v_exp_f32_e32 v1, v1
	v_cndmask_b32_e32 v154, v0, v189, vcc
	v_mov_b32_e32 v131, v8
	v_pk_add_f32 v[64:65], v[130:131], v[154:155] op_sel_hi:[1,0] neg_lo:[0,1] neg_hi:[0,1]
	v_cndmask_b32_e64 v147, v1, 1.0, vcc
	v_exp_f32_e32 v221, v64
	v_mov_b32_e32 v0, v9
	v_mov_b32_e32 v1, v10
	v_pk_add_f32 v[66:67], v[0:1], v[154:155] op_sel_hi:[1,0] neg_lo:[0,1] neg_hi:[0,1]
	v_mov_b32_e32 v0, v11
	v_mov_b32_e32 v1, v12
	v_pk_add_f32 v[68:69], v[0:1], v[154:155] op_sel_hi:[1,0] neg_lo:[0,1] neg_hi:[0,1]
	v_mov_b32_e32 v0, v13
	v_mov_b32_e32 v1, v14
	v_sub_f32_e32 v165, v15, v154
	v_pk_add_f32 v[70:71], v[0:1], v[154:155] op_sel_hi:[1,0] neg_lo:[0,1] neg_hi:[0,1]
	s_mov_b32 s77, s14
	s_add_i32 s4, s4, s14
	s_add_i32 s3, s8, s3
	v_readlane_b32 s8, v248, 29
	v_readlane_b32 s9, v248, 30
	v_readlane_b32 s10, v248, 31
	v_readlane_b32 s11, v248, 32
	v_readlane_b32 s12, v248, 33
	v_readlane_b32 s13, v248, 34
	v_or_b32_e32 v0, s4, v199
	v_readlane_b32 s4, v247, 3
	v_readlane_b32 s14, v248, 35
	v_readlane_b32 s15, v248, 36
	s_mov_b64 s[8:9], s[12:13]
	v_sub_u32_e32 v216, v0, v201
	v_add_u32_e32 v197, s4, v146
	v_or3_b32 v0, v16, v200, s5
	v_lshlrev_b32_e32 v1, 1, v155
	s_mul_hi_i32 s4, s3, 0x104000
	s_mul_i32 s3, s3, 0x104000
	s_mov_b64 s[10:11], s[14:15]
	s_waitcnt vmcnt(4) lgkmcnt(0)
	s_barrier
	v_lshlrev_b32_e32 v0, 8, v0
	v_and_b32_e32 v211, 64, v1
	v_and_b32_e32 v210, 48, v22
	s_add_u32 s82, s10, s3
	v_bitop3_b32 v212, v17, s16, v190 bitop3:0xc8
	v_mov_b32_e32 v48, v129
	v_mov_b32_e32 v49, v129
	v_or3_b32 v150, v0, v211, v210
	s_addc_u32 s83, s11, s4
	v_or3_b32 v152, v0, v212, v210
	v_mov_b32_e32 v50, v129
	v_mov_b32_e32 v51, v129
	v_mov_b32_e32 v52, v129
	v_mov_b32_e32 v53, v129
	v_mov_b32_e32 v54, v129
	v_mov_b32_e32 v55, v129
	v_mov_b32_e32 v56, v129
	v_mov_b32_e32 v57, v129
	v_mov_b32_e32 v58, v129
	v_mov_b32_e32 v59, v129
	v_mov_b32_e32 v60, v129
	v_mov_b32_e32 v61, v129
	v_mov_b32_e32 v62, v129
	v_mov_b32_e32 v63, v129
	v_mov_b64_e32 v[32:33], v[48:49]
	v_mov_b64_e32 v[16:17], v[48:49]
	v_mov_b64_e32 v[0:1], v[48:49]
	v_lshl_add_u32 v214, v199, 2, s6
	v_add_u32_e32 v131, s6, v146
	v_mov_b32_e32 v151, v129
	v_mov_b32_e32 v153, v129
	v_mov_b32_e32 v215, 0
	s_mov_b32 s76, 0x8000
	s_movk_i32 s92, 0xbf
	s_mov_b64 s[68:69], s[82:83]
	v_mov_b32_e32 v217, v197
	v_mov_b64_e32 v[34:35], v[50:51]
	v_mov_b64_e32 v[36:37], v[52:53]
	v_mov_b64_e32 v[38:39], v[54:55]
	v_mov_b64_e32 v[40:41], v[56:57]
	v_mov_b64_e32 v[42:43], v[58:59]
	v_mov_b64_e32 v[44:45], v[60:61]
	v_mov_b64_e32 v[46:47], v[62:63]
	v_mov_b64_e32 v[18:19], v[50:51]
	v_mov_b64_e32 v[20:21], v[52:53]
	v_mov_b64_e32 v[22:23], v[54:55]
	v_mov_b64_e32 v[24:25], v[56:57]
	v_mov_b64_e32 v[26:27], v[58:59]
	v_mov_b64_e32 v[28:29], v[60:61]
	v_mov_b64_e32 v[30:31], v[62:63]
	v_mov_b64_e32 v[2:3], v[50:51]
	v_mov_b64_e32 v[4:5], v[52:53]
	v_mov_b64_e32 v[6:7], v[54:55]
	v_mov_b64_e32 v[8:9], v[56:57]
	v_mov_b64_e32 v[10:11], v[58:59]
	v_mov_b64_e32 v[12:13], v[60:61]
	v_mov_b64_e32 v[14:15], v[62:63]
	s_mov_b32 s72, 0
	v_mov_b32_e32 v236, v221
	v_mov_b32_e32 v233, v221
	v_mov_b32_e32 v235, v221
	v_mov_b32_e32 v231, v221
	v_mov_b32_e32 v234, v221
	v_mov_b32_e32 v230, v221
	v_mov_b32_e32 v232, v221
	v_mov_b32_e32 v227, v221
	v_mov_b32_e32 v229, v221
	v_mov_b32_e32 v225, v221
	v_mov_b32_e32 v228, v221
	v_mov_b32_e32 v223, v221
	v_mov_b32_e32 v226, v221
	v_mov_b32_e32 v222, v221
	v_mov_b32_e32 v224, v221
	v_mov_b32_e32 v168, v64
	v_mov_b32_e32 v169, v64
	v_mov_b32_e32 v172, v64
	v_mov_b32_e32 v173, v64
	v_mov_b32_e32 v176, v64
	v_mov_b32_e32 v177, v64
	v_mov_b32_e32 v166, v64
	v_mov_b32_e32 v167, v64
	v_mov_b32_e32 v170, v65
	v_mov_b32_e32 v171, v66
	v_mov_b32_e32 v174, v67
	v_mov_b32_e32 v175, v68
	v_mov_b32_e32 v178, v69
	v_mov_b32_e32 v179, v70
	v_mov_b32_e32 v164, v71

; #define LAS __attribute__((address_space(3)))
; __device__ __forceinline__ void finishSM(f32x16& p0, f32x16& p1, float alpha, float& l_reg, bf16x8& pa0, bf16x8& pa1, bf16x8& pa2, bf16x8& pa3) {
; #pragma unroll
;     for (int r = 0; r < 16; ++r) p1[r] = __builtin_amdgcn_exp2f(p1[r]);
;     float ps = 0;
; #pragma unroll
;     for (int r = 0; r < 16; ++r) ps += p0[r];
; #pragma unroll
;     for (int r = 0; r < 16; ++r) ps += p1[r];
;     { auto rr = __builtin_amdgcn_permlane32_swap(__float_as_uint(ps), __float_as_uint(ps), false, false);
;       ps = __uint_as_float(rr[0]) + __uint_as_float(rr[1]); }
;     l_reg = l_reg * alpha + ps;
;     ...
;     PK4(p0, 0, pa0); PK4(p0, 8, pa1); PK4(p1, 0, pa2); PK4(p1, 8, pa3);
; __device__ __forceinline__ void qkt(f32x16& p0, f32x16& p1, const char* Kslot, int r32, int hi, const bf16x8* qr, const LAS f32x4* cp) {
; #pragma unroll
;     for (int g = 0; g < 4; ++g) { const f32x4 c0 = cp[2 * g], c1 = cp[8 + 2 * g];
; #pragma unroll
;         for (int j = 0; j < 4; ++j) { p0[4 * g + j] = c0[j]; p1[4 * g + j] = c1[j]; } }
;     const char* kb[4];
; #pragma unroll
;     for (int dd = 0; dd < 4; ++dd) kb[dd] = Kslot + KSWZ(r32, (dd * 16 + hi * 8) * 2);
; #pragma unroll
;     for (int d0 = 0; d0 < 8; ++d0) { const char* a = kb[d0 & 3] + (d0 >> 2) * 128;
;         bf16x8 b0 = *reinterpret_cast<const bf16x8*>(a);
;         bf16x8 b1 = *reinterpret_cast<const bf16x8*>(a + 32 * 256);
;         p0 = __builtin_amdgcn_mfma_f32_32x32x16_bf16(b0, qr[d0], p0, 0, 0, 0);
;         p1 = __builtin_amdgcn_mfma_f32_32x32x16_bf16(b1, qr[d0], p1, 0, 0, 0); }
; }
.LBB0_523:
	s_add_i32 s3, s70, s76
	v_lshl_add_u64 v[160:161], s[68:69], 0, v[150:151]
	v_lshl_add_u64 v[64:65], v[160:161], 0, s[84:85]
	s_mov_b32 m0, s3
	v_lshl_add_u64 v[162:163], s[68:69], 0, v[152:153]
	global_load_lds_dwordx4 v[64:65], off
	v_lshl_add_u64 v[64:65], v[162:163], 0, s[84:85]
	s_add_i32 m0, s3, 0x400
	s_nop 0
	global_load_lds_dwordx4 v[64:65], off
	s_add_i32 s3, s73, 0
	v_add_u32_e32 v218, s3, v193
	ds_read_b128 v[80:83], v217
	ds_read_b128 v[84:87], v217 offset:32
	ds_read_b128 v[64:67], v217 offset:128
	ds_read_b128 v[68:71], v217 offset:160
	ds_read_b128 v[88:91], v217 offset:64
	ds_read_b128 v[72:75], v217 offset:192
	ds_read_b128 v[92:95], v217 offset:96
	ds_read_b128 v[76:79], v217 offset:224
	ds_read_b128 v[238:241], v218 offset:49152
	ds_read_b128 v[242:245], v218 offset:57344
	v_add_u32_e32 v219, s3, v194
	v_add_u32_e32 v220, s3, v195
	s_waitcnt lgkmcnt(0)
	v_mfma_f32_32x32x16_bf16 v[80:95], v[238:241], v[96:99], v[80:95]
	v_add_u32_e32 v237, s3, v196
	v_exp_f32_e32 v173, v173
	v_exp_f32_e32 v176, v176
	v_exp_f32_e32 v177, v177
	v_exp_f32_e32 v178, v178
	v_exp_f32_e32 v179, v179
	v_exp_f32_e32 v246, v165
	v_mfma_f32_32x32x16_bf16 v[64:79], v[242:245], v[96:99], v[64:79]
	ds_read_b128 v[238:241], v219 offset:49152
	ds_read_b128 v[242:245], v219 offset:57344
	s_waitcnt lgkmcnt(0)
	v_mfma_f32_32x32x16_bf16 v[64:79], v[242:245], v[100:103], v[64:79]
	v_mfma_f32_32x32x16_bf16 v[80:95], v[238:241], v[100:103], v[80:95]
	ds_read_b128 v[238:241], v220 offset:49152
	ds_read_b128 v[242:245], v220 offset:57344
	s_waitcnt lgkmcnt(0)
	v_mfma_f32_32x32x16_bf16 v[64:79], v[242:245], v[104:107], v[64:79]
	v_mfma_f32_32x32x16_bf16 v[80:95], v[238:241], v[104:107], v[80:95]
	ds_read_b128 v[238:241], v237 offset:49152
	ds_read_b128 v[242:245], v237 offset:57344
	s_waitcnt lgkmcnt(0)
	v_mfma_f32_32x32x16_bf16 v[64:79], v[242:245], v[108:111], v[64:79]
	v_mfma_f32_32x32x16_bf16 v[80:95], v[238:241], v[108:111], v[80:95]
	v_xor_b32_e32 v249, 0x80, v218
	v_xor_b32_e32 v250, 0x80, v219
	v_xor_b32_e32 v251, 0x80, v220
	v_xor_b32_e32 v252, 0x80, v237
	ds_read_b128 v[238:241], v249 offset:49152
	ds_read_b128 v[242:245], v249 offset:57344
	s_waitcnt lgkmcnt(0)
	v_mfma_f32_32x32x16_bf16 v[64:79], v[242:245], v[112:115], v[64:79]
	v_mfma_f32_32x32x16_bf16 v[80:95], v[238:241], v[112:115], v[80:95]
	ds_read_b128 v[238:241], v250 offset:49152
	ds_read_b128 v[242:245], v250 offset:57344
	s_waitcnt lgkmcnt(0)
	v_mfma_f32_32x32x16_bf16 v[64:79], v[242:245], v[116:119], v[64:79]
	v_mfma_f32_32x32x16_bf16 v[80:95], v[238:241], v[116:119], v[80:95]
	ds_read_b128 v[238:241], v251 offset:49152
	ds_read_b128 v[242:245], v251 offset:57344
	v_exp_f32_e32 v220, v168
	s_waitcnt lgkmcnt(0)
	v_mfma_f32_32x32x16_bf16 v[64:79], v[242:245], v[120:123], v[64:79]
	v_mfma_f32_32x32x16_bf16 v[80:95], v[238:241], v[120:123], v[80:95]
	ds_read_b128 v[238:241], v252 offset:49152
	ds_read_b128 v[242:245], v252 offset:57344
	v_exp_f32_e32 v237, v169
	s_waitcnt lgkmcnt(0)
	v_mfma_f32_32x32x16_bf16 v[64:79], v[242:245], v[124:127], v[64:79]
	v_exp_f32_e32 v245, v164
	v_add_f32_e32 v164, 0, v221
	v_add_f32_e32 v164, v236, v164
	v_add_f32_e32 v164, v233, v164
	v_add_f32_e32 v164, v235, v164
	v_add_f32_e32 v164, v231, v164
	v_add_f32_e32 v164, v234, v164
	v_add_f32_e32 v164, v230, v164
	v_add_f32_e32 v164, v232, v164
	v_add_f32_e32 v164, v227, v164
	v_add_f32_e32 v164, v229, v164
	v_add_f32_e32 v164, v225, v164
	v_add_f32_e32 v164, v228, v164
	v_add_f32_e32 v164, v223, v164
	v_add_f32_e32 v164, v226, v164
	v_mfma_f32_32x32x16_bf16 v[80:95], v[238:241], v[124:127], v[80:95]
	v_exp_f32_e32 v238, v172
	v_add_f32_e32 v164, v222, v164
	v_add_f32_e32 v164, v224, v164
	v_add_f32_e32 v164, v220, v164
	v_add_f32_e32 v164, v237, v164
	v_exp_f32_e32 v239, v166
	v_add_f32_e32 v164, v238, v164
	v_exp_f32_e32 v240, v167
	v_add_f32_e32 v164, v173, v164
	v_exp_f32_e32 v241, v170
	v_add_f32_e32 v164, v176, v164
	v_exp_f32_e32 v242, v171
	v_add_f32_e32 v164, v177, v164
	v_exp_f32_e32 v243, v174
	v_add_f32_e32 v164, v239, v164
	v_exp_f32_e32 v244, v175
	v_add_f32_e32 v164, v240, v164
	v_add_f32_e32 v164, v241, v164
	v_add_f32_e32 v164, v242, v164
	v_add_f32_e32 v164, v243, v164
	v_add_f32_e32 v164, v244, v164
	v_add_f32_e32 v164, v178, v164
	v_add_f32_e32 v164, v179, v164
	v_add_f32_e32 v164, v245, v164
	v_add_f32_e32 v218, v246, v164
	v_mov_b32_e32 v219, v218
	s_nop 1
	v_permlane32_swap_b32_e32 v218, v219
	v_cvt_pk_bf16_f32 v164, v221, v236
	v_cvt_pk_bf16_f32 v165, v233, v235
	v_cvt_pk_bf16_f32 v166, v231, v234
	v_cvt_pk_bf16_f32 v167, v230, v232
	v_cvt_pk_bf16_f32 v168, v227, v229
	v_cvt_pk_bf16_f32 v169, v225, v228
	v_cvt_pk_bf16_f32 v170, v223, v226
	v_cvt_pk_bf16_f32 v171, v222, v224
	v_cvt_pk_bf16_f32 v172, v220, v237
	v_cvt_pk_bf16_f32 v173, v238, v173
	v_cvt_pk_bf16_f32 v174, v176, v177
	v_cvt_pk_bf16_f32 v175, v239, v240
	v_cvt_pk_bf16_f32 v176, v241, v242
	v_cvt_pk_bf16_f32 v177, v243, v244
	v_cvt_pk_bf16_f32 v178, v178, v179
	v_cvt_pk_bf16_f32 v179, v245, v246
	s_nop 0
	v_permlane32_swap_b32_e32 v164, v166
	v_permlane32_swap_b32_e32 v165, v167
	v_permlane32_swap_b32_e32 v168, v170
	v_permlane32_swap_b32_e32 v169, v171
	v_permlane32_swap_b32_e32 v172, v174
	v_permlane32_swap_b32_e32 v173, v175
	v_permlane32_swap_b32_e32 v176, v178
	v_permlane32_swap_b32_e32 v177, v179
	v_add_u32_e32 v236, s2, v192
	ds_read_b64_tr_b16 v[220:221], v236 offset:0
	ds_read_b64_tr_b16 v[222:223], v236 offset:0x800
	ds_read_b64_tr_b16 v[224:225], v236 offset:0x1000
	ds_read_b64_tr_b16 v[226:227], v236 offset:0x1800
	ds_read_b64_tr_b16 v[228:229], v236 offset:0x2000
	ds_read_b64_tr_b16 v[230:231], v236 offset:0x2800
	ds_read_b64_tr_b16 v[232:233], v236 offset:0x3000
	ds_read_b64_tr_b16 v[234:235], v236 offset:0x3800
	s_waitcnt lgkmcnt(4)
; #define SBAR() __builtin_amdgcn_sched_barrier(0)
; #define PV_RD(d0, kh, X) do { constexpr int b_ = v_rd_off(d0, 2 * (kh), 0); TRRD(X##l0, b_); TRRD(X##h0, b_ + 2048); TRRD(X##l1, b_ + 4096); TRRD(X##h1, b_ + 6144); } while (0)
; #define PV_MM(d0, X, PA, PB) do { \
;         o[d0] = __builtin_amdgcn_mfma_f32_32x32x16_bf16(PA, (bf16x8){X##l0[0], X##l0[1], X##l0[2], X##l0[3], X##h0[0], X##h0[1], X##h0[2], X##h0[3]}, o[d0], 0, 0, 0);   \
;         o[d0] = __builtin_amdgcn_mfma_f32_32x32x16_bf16(PB, (bf16x8){X##l1[0], X##l1[1], X##l1[2], X##l1[3], X##h1[0], X##h1[1], X##h1[2], X##h1[3]}, o[d0], 0, 0, 0); } while (0)
; #define PV_W4() do { asm volatile("s_waitcnt lgkmcnt(4)" ::: "memory"); SBAR(); } while (0)
; #define PV_W0() do { asm volatile("s_waitcnt lgkmcnt(0)" ::: "memory"); SBAR(); } while (0)
; __device__ __forceinline__ void mask_tile(f32x16& p0, f32x16& p1, int dq) {
;     const float NEG = -__builtin_inff();
; #pragma unroll
;     for (int r = 0; r < 16; ++r) { const int c = (r & 3) + 8 * (r >> 2); if (dq - c < 0) p0[r] = NEG; if (dq - c - 32 < 0) p1[r] = NEG; }
; }
; __device__ __forceinline__ void pv_tile(f32x16* o, int vb0, bf16x8 pa0, bf16x8 pa1, bf16x8 pa2, bf16x8 pa3) {
;     ...
;     s16x4 al0, al1, ah0, ah1, bl0, bl1, bh0, bh1;
;     PV_RD(0, 0, a);
;     PV_RD(0, 1, b); PV_W4(); PV_MM(0, a, pa0, pa1); SBAR();
;     PV_RD(1, 0, a); PV_W4(); PV_MM(0, b, pa2, pa3); SBAR();
;     PV_RD(1, 1, b); PV_W4(); PV_MM(1, a, pa0, pa1); SBAR();
;     PV_RD(2, 0, a); PV_W4(); PV_MM(1, b, pa2, pa3); SBAR();
;     PV_RD(2, 1, b); PV_W4(); PV_MM(2, a, pa0, pa1); SBAR();
;     PV_RD(3, 0, a); PV_W4(); PV_MM(2, b, pa2, pa3); SBAR();
;     PV_RD(3, 1, b); PV_W4(); PV_MM(3, a, pa0, pa1); SBAR();
;     PV_W0(); PV_MM(3, b, pa2, pa3);
	s_nop 0
	v_mfma_f32_32x32x16_bf16 v[48:63], v[164:167], v[220:223], v[48:63]
	v_mfma_f32_32x32x16_bf16 v[48:63], v[168:171], v[224:227], v[48:63]
	ds_read_b64_tr_b16 v[220:221], v236 offset:0x200
	ds_read_b64_tr_b16 v[222:223], v236 offset:0xa00
	ds_read_b64_tr_b16 v[224:225], v236 offset:0x1200
	ds_read_b64_tr_b16 v[226:227], v236 offset:0x1a00
	s_waitcnt lgkmcnt(4)
	v_mfma_f32_32x32x16_bf16 v[48:63], v[172:175], v[228:231], v[48:63]
	v_mfma_f32_32x32x16_bf16 v[48:63], v[176:179], v[232:235], v[48:63]
	ds_read_b64_tr_b16 v[228:229], v236 offset:0x2200
	ds_read_b64_tr_b16 v[230:231], v236 offset:0x2a00
	ds_read_b64_tr_b16 v[232:233], v236 offset:0x3200
	ds_read_b64_tr_b16 v[234:235], v236 offset:0x3a00
	s_waitcnt lgkmcnt(4)
	v_mfma_f32_32x32x16_bf16 v[32:47], v[164:167], v[220:223], v[32:47]
	v_mfma_f32_32x32x16_bf16 v[32:47], v[168:171], v[224:227], v[32:47]
	ds_read_b64_tr_b16 v[220:221], v236 offset:0x400
	ds_read_b64_tr_b16 v[222:223], v236 offset:0xc00
	ds_read_b64_tr_b16 v[224:225], v236 offset:0x1400
	ds_read_b64_tr_b16 v[226:227], v236 offset:0x1c00
	s_waitcnt lgkmcnt(4)
	v_mfma_f32_32x32x16_bf16 v[32:47], v[172:175], v[228:231], v[32:47]
	v_mfma_f32_32x32x16_bf16 v[32:47], v[176:179], v[232:235], v[32:47]
	ds_read_b64_tr_b16 v[228:229], v236 offset:0x2400
	ds_read_b64_tr_b16 v[230:231], v236 offset:0x2c00
	ds_read_b64_tr_b16 v[232:233], v236 offset:0x3400
	ds_read_b64_tr_b16 v[234:235], v236 offset:0x3c00
	s_waitcnt lgkmcnt(4)
	v_mfma_f32_32x32x16_bf16 v[16:31], v[164:167], v[220:223], v[16:31]
	v_mfma_f32_32x32x16_bf16 v[16:31], v[168:171], v[224:227], v[16:31]
	ds_read_b64_tr_b16 v[220:221], v236 offset:0x600
	ds_read_b64_tr_b16 v[222:223], v236 offset:0xe00
	ds_read_b64_tr_b16 v[224:225], v236 offset:0x1600
	ds_read_b64_tr_b16 v[226:227], v236 offset:0x1e00
	s_waitcnt lgkmcnt(4)
	v_mfma_f32_32x32x16_bf16 v[16:31], v[172:175], v[228:231], v[16:31]
	v_mfma_f32_32x32x16_bf16 v[16:31], v[176:179], v[232:235], v[16:31]
	ds_read_b64_tr_b16 v[228:229], v236 offset:0x2600
	ds_read_b64_tr_b16 v[230:231], v236 offset:0x2e00
	ds_read_b64_tr_b16 v[232:233], v236 offset:0x3600
	ds_read_b64_tr_b16 v[234:235], v236 offset:0x3e00
	s_waitcnt lgkmcnt(4)
	v_mfma_f32_32x32x16_bf16 v[0:15], v[164:167], v[220:223], v[0:15]
	v_mfma_f32_32x32x16_bf16 v[0:15], v[168:171], v[224:227], v[0:15]
	s_waitcnt lgkmcnt(0)
	v_mfma_f32_32x32x16_bf16 v[0:15], v[172:175], v[228:231], v[0:15]
	s_sub_i32 s2, s92, 64
	s_cmp_le_i32 s2, s91
	v_mfma_f32_32x32x16_bf16 v[0:15], v[176:179], v[232:235], v[0:15]
	s_cbranch_scc1 .LBB0_525
	v_cmp_gt_i32_e64 s[62:63], 26, v216
	v_cmp_gt_i32_e64 s[64:65], 27, v216
	v_cmp_gt_i32_e64 s[60:61], 25, v216
	s_and_b64 s[62:63], s[64:65], s[62:63]
	v_cmp_gt_i32_e64 s[58:59], 24, v216
	s_and_b64 s[60:61], s[62:63], s[60:61]
	v_cmp_gt_i32_e64 s[56:57], 19, v216
	s_and_b64 s[58:59], s[60:61], s[58:59]
	v_cmp_gt_i32_e64 s[54:55], 18, v216
	s_and_b64 s[56:57], s[58:59], s[56:57]
	v_cmp_gt_i32_e64 s[52:53], 17, v216
	s_and_b64 s[54:55], s[56:57], s[54:55]
	v_cmp_gt_i32_e64 s[50:51], 16, v216
	s_and_b64 s[52:53], s[54:55], s[52:53]
	v_cmp_gt_i32_e64 s[48:49], 11, v216
	s_and_b64 s[50:51], s[52:53], s[50:51]
	v_cmp_gt_i32_e64 s[46:47], 10, v216
	s_and_b64 s[48:49], s[50:51], s[48:49]
	v_cmp_gt_i32_e64 s[44:45], 9, v216
	s_and_b64 s[46:47], s[48:49], s[46:47]
	v_cmp_gt_i32_e64 s[42:43], 8, v216
	s_and_b64 s[44:45], s[46:47], s[44:45]
	v_cmp_gt_i32_e64 s[40:41], 3, v216
	s_and_b64 s[42:43], s[44:45], s[42:43]
	v_cmp_gt_i32_e64 s[38:39], 2, v216
	s_and_b64 s[40:41], s[42:43], s[40:41]
	v_cmp_gt_i32_e64 s[36:37], 1, v216
	s_and_b64 s[38:39], s[40:41], s[38:39]
	v_cmp_gt_i32_e64 s[34:35], 0, v216
	s_and_b64 s[36:37], s[38:39], s[36:37]
	s_and_b64 s[34:35], s[36:37], s[34:35]
	v_cmp_gt_i32_e64 s[28:29], 58, v216
	v_cndmask_b32_e64 v80, v80, v130, s[34:35]
	v_cmp_gt_i32_e64 s[34:35], 59, v216
	v_cmp_gt_i32_e64 s[26:27], 57, v216
	s_and_b64 s[28:29], s[34:35], s[28:29]
	v_cmp_gt_i32_e64 s[24:25], 56, v216
	s_and_b64 s[26:27], s[28:29], s[26:27]
	v_cmp_gt_i32_e64 s[22:23], 51, v216
	s_and_b64 s[24:25], s[26:27], s[24:25]
	v_cmp_gt_i32_e64 s[20:21], 50, v216
	s_and_b64 s[22:23], s[24:25], s[22:23]
	v_cmp_gt_i32_e64 s[18:19], 49, v216
	s_and_b64 s[20:21], s[22:23], s[20:21]
	v_cmp_gt_i32_e64 s[16:17], 48, v216
	s_and_b64 s[18:19], s[20:21], s[18:19]
	v_cmp_gt_i32_e64 s[14:15], 43, v216
	s_and_b64 s[16:17], s[18:19], s[16:17]
	v_cmp_gt_i32_e64 s[12:13], 42, v216
	s_and_b64 s[14:15], s[16:17], s[14:15]
	v_cmp_gt_i32_e64 s[10:11], 41, v216
	s_and_b64 s[12:13], s[14:15], s[12:13]
	v_cmp_gt_i32_e64 s[8:9], 40, v216
	s_and_b64 s[10:11], s[12:13], s[10:11]
	v_cmp_gt_i32_e64 s[6:7], 35, v216
	s_and_b64 s[8:9], s[10:11], s[8:9]
	v_cmp_gt_i32_e64 s[4:5], 34, v216
	s_and_b64 s[6:7], s[8:9], s[6:7]
	v_cmp_gt_i32_e64 s[2:3], 33, v216
	s_and_b64 s[4:5], s[6:7], s[4:5]
	v_cmp_gt_i32_e32 vcc, 32, v216
	s_and_b64 s[2:3], s[4:5], s[2:3]
	s_and_b64 vcc, s[2:3], vcc
	v_cndmask_b32_e64 v95, v95, v130, s[64:65]
	v_cndmask_b32_e64 v94, v94, v130, s[62:63]
	v_cndmask_b32_e64 v93, v93, v130, s[60:61]
	v_cndmask_b32_e64 v92, v92, v130, s[58:59]
	v_cndmask_b32_e64 v91, v91, v130, s[56:57]
	v_cndmask_b32_e64 v90, v90, v130, s[54:55]
	v_cndmask_b32_e64 v89, v89, v130, s[52:53]
	v_cndmask_b32_e64 v88, v88, v130, s[50:51]
	v_cndmask_b32_e64 v87, v87, v130, s[48:49]
	v_cndmask_b32_e64 v86, v86, v130, s[46:47]
	v_cndmask_b32_e64 v85, v85, v130, s[44:45]
	v_cndmask_b32_e64 v84, v84, v130, s[42:43]
	v_cndmask_b32_e64 v83, v83, v130, s[40:41]
	v_cndmask_b32_e64 v82, v82, v130, s[38:39]
	v_cndmask_b32_e64 v81, v81, v130, s[36:37]
	v_cndmask_b32_e64 v79, v79, v130, s[34:35]
	v_cndmask_b32_e64 v78, v78, v130, s[28:29]
	v_cndmask_b32_e64 v77, v77, v130, s[26:27]
	v_cndmask_b32_e64 v76, v76, v130, s[24:25]
	v_cndmask_b32_e64 v75, v75, v130, s[22:23]
	v_cndmask_b32_e64 v74, v74, v130, s[20:21]
	v_cndmask_b32_e64 v73, v73, v130, s[18:19]
	v_cndmask_b32_e64 v72, v72, v130, s[16:17]
	v_cndmask_b32_e64 v71, v71, v130, s[14:15]
	v_cndmask_b32_e64 v70, v70, v130, s[12:13]
	v_cndmask_b32_e64 v69, v69, v130, s[10:11]
	v_cndmask_b32_e64 v68, v68, v130, s[8:9]
	v_cndmask_b32_e64 v67, v67, v130, s[6:7]
	v_cndmask_b32_e64 v66, v66, v130, s[4:5]
	v_cndmask_b32_e64 v65, v65, v130, s[2:3]
	v_cndmask_b32_e32 v64, v64, v130, vcc

; #define LAS __attribute__((address_space(3)))
; __device__ __forceinline__ void partialSM(f32x16& p0, f32x16& p1, float& m_reg, float& mn, float& alpha) {
;     float pmax = p0[0];
; #pragma unroll
;     for (int r = 1; r < 16; ++r) pmax = fmaxf(pmax, p0[r]);
; #pragma unroll
;     for (int r = 0; r < 16; ++r) pmax = fmaxf(pmax, p1[r]);
;     { auto rr = __builtin_amdgcn_permlane32_swap(__float_as_uint(pmax), __float_as_uint(pmax), false, false);
;       pmax = fmaxf(__uint_as_float(rr[0]), __uint_as_float(rr[1])); }
;     if (__builtin_expect(__all((pmax - m_reg) <= THR2), 1)) { mn = m_reg; alpha = 1.f; }
;     else { mn = fmaxf(m_reg, pmax); alpha = __builtin_amdgcn_exp2f(m_reg - mn); m_reg = mn; }
; #pragma unroll
;     for (int r = 0; r < 16; ++r) p0[r] = p0[r] - mn;
; #pragma unroll
;     for (int r = 0; r < 16; ++r) p1[r] = p1[r] - mn;
; #pragma unroll
;     for (int r = 0; r < 16; ++r) p0[r] = __builtin_amdgcn_exp2f(p0[r]);
; }
; __device__ __forceinline__ void qkt(f32x16& p0, f32x16& p1, const char* Kslot, int r32, int hi, const bf16x8* qr, const LAS f32x4* cp) {
; #pragma unroll
;     for (int g = 0; g < 4; ++g) { const f32x4 c0 = cp[2 * g], c1 = cp[8 + 2 * g];
; #pragma unroll
;         for (int j = 0; j < 4; ++j) { p0[4 * g + j] = c0[j]; p1[4 * g + j] = c1[j]; } }
;     const char* kb[4];
; #pragma unroll
;     for (int dd = 0; dd < 4; ++dd) kb[dd] = Kslot + KSWZ(r32, (dd * 16 + hi * 8) * 2);
; #pragma unroll
;     for (int d0 = 0; d0 < 8; ++d0) { const char* a = kb[d0 & 3] + (d0 >> 2) * 128;
;         bf16x8 b0 = *reinterpret_cast<const bf16x8*>(a);
;         bf16x8 b1 = *reinterpret_cast<const bf16x8*>(a + 32 * 256);
;         p0 = __builtin_amdgcn_mfma_f32_32x32x16_bf16(b0, qr[d0], p0, 0, 0, 0);
;         p1 = __builtin_amdgcn_mfma_f32_32x32x16_bf16(b1, qr[d0], p1, 0, 0, 0); }
; }
.LBB0_537:
	v_cndmask_b32_e64 v154, v164, v154, s[2:3]
	v_sub_f32_e32 v80, v80, v154
	v_sub_f32_e32 v81, v81, v154
	v_sub_f32_e32 v82, v82, v154
	v_sub_f32_e32 v83, v83, v154
	v_sub_f32_e32 v84, v84, v154
	v_sub_f32_e32 v85, v85, v154
	v_sub_f32_e32 v86, v86, v154
	v_sub_f32_e32 v87, v87, v154
	v_sub_f32_e32 v88, v88, v154
	v_sub_f32_e32 v89, v89, v154
	v_sub_f32_e32 v90, v90, v154
	v_sub_f32_e32 v91, v91, v154
	v_sub_f32_e32 v92, v92, v154
	v_sub_f32_e32 v93, v93, v154
	v_sub_f32_e32 v94, v94, v154
	v_sub_f32_e32 v95, v95, v154
	v_sub_f32_e32 v164, v64, v154
	v_sub_f32_e32 v165, v65, v154
	v_sub_f32_e32 v166, v66, v154
	v_sub_f32_e32 v167, v67, v154
	v_sub_f32_e32 v168, v68, v154
	v_sub_f32_e32 v169, v69, v154
	v_sub_f32_e32 v170, v70, v154
	v_sub_f32_e32 v171, v71, v154
	v_sub_f32_e32 v172, v72, v154
	v_sub_f32_e32 v173, v73, v154
	v_sub_f32_e32 v174, v74, v154
	v_sub_f32_e32 v175, v75, v154
	v_sub_f32_e32 v176, v76, v154
	v_exp_f32_e32 v177, v80
	v_exp_f32_e32 v178, v81
	v_exp_f32_e32 v179, v82
	v_exp_f32_e32 v221, v83
	v_exp_f32_e32 v222, v84
	v_exp_f32_e32 v223, v85
	v_exp_f32_e32 v224, v86
	v_exp_f32_e32 v225, v87
	v_exp_f32_e32 v226, v88
	v_exp_f32_e32 v227, v89
	v_exp_f32_e32 v228, v90
	v_exp_f32_e32 v229, v91
	v_exp_f32_e32 v230, v92
	v_exp_f32_e32 v231, v93
	v_exp_f32_e32 v232, v94
	v_exp_f32_e32 v233, v95
	v_sub_f32_e32 v234, v77, v154
	v_sub_f32_e32 v235, v78, v154
	v_sub_f32_e32 v236, v79, v154
	s_add_i32 s2, s76, 0
	v_add_u32_e32 v237, s2, v193
	ds_read_b128 v[80:83], v217 offset:256
	ds_read_b128 v[84:87], v217 offset:288
	ds_read_b128 v[64:67], v217 offset:384
	ds_read_b128 v[68:71], v217 offset:416
	ds_read_b128 v[88:91], v217 offset:320
	ds_read_b128 v[72:75], v217 offset:448
	ds_read_b128 v[92:95], v217 offset:352
	ds_read_b128 v[76:79], v217 offset:480
	ds_read_b128 v[156:159], v237 offset:49152
	ds_read_b128 v[160:163], v237 offset:57344
	v_add_u32_e32 v238, s2, v194
	v_add_u32_e32 v239, s2, v195
	s_waitcnt lgkmcnt(0)
	v_mfma_f32_32x32x16_bf16 v[80:95], v[156:159], v[96:99], v[80:95]
	v_add_u32_e32 v240, s2, v196
	v_exp_f32_e32 v167, v167
	v_exp_f32_e32 v168, v168
	v_exp_f32_e32 v169, v169
	v_exp_f32_e32 v170, v170
	v_exp_f32_e32 v171, v171
	v_exp_f32_e32 v172, v172
	v_mfma_f32_32x32x16_bf16 v[64:79], v[160:163], v[96:99], v[64:79]
	ds_read_b128 v[156:159], v238 offset:49152
	ds_read_b128 v[160:163], v238 offset:57344
	v_exp_f32_e32 v173, v173
	v_exp_f32_e32 v174, v174
	v_exp_f32_e32 v175, v175
	v_exp_f32_e32 v176, v176
	v_exp_f32_e32 v234, v234
	v_exp_f32_e32 v235, v235
	s_waitcnt lgkmcnt(0)
	v_mfma_f32_32x32x16_bf16 v[80:95], v[156:159], v[100:103], v[80:95]
	v_exp_f32_e32 v236, v236
	v_mfma_f32_32x32x16_bf16 v[64:79], v[160:163], v[100:103], v[64:79]
	ds_read_b128 v[156:159], v239 offset:49152
	ds_read_b128 v[160:163], v239 offset:57344
	s_waitcnt lgkmcnt(0)
	v_mfma_f32_32x32x16_bf16 v[80:95], v[156:159], v[104:107], v[80:95]
	v_mfma_f32_32x32x16_bf16 v[64:79], v[160:163], v[104:107], v[64:79]
	ds_read_b128 v[156:159], v240 offset:49152
	ds_read_b128 v[160:163], v240 offset:57344
	s_waitcnt lgkmcnt(0)
	v_mfma_f32_32x32x16_bf16 v[80:95], v[156:159], v[108:111], v[80:95]
	v_mfma_f32_32x32x16_bf16 v[64:79], v[160:163], v[108:111], v[64:79]
	v_xor_b32_e32 v249, 0x80, v237
	v_xor_b32_e32 v250, 0x80, v238
	v_xor_b32_e32 v251, 0x80, v239
	v_xor_b32_e32 v252, 0x80, v240
	ds_read_b128 v[156:159], v249 offset:49152
	ds_read_b128 v[160:163], v249 offset:57344
	v_exp_f32_e32 v237, v164
	s_waitcnt lgkmcnt(0)
	v_mfma_f32_32x32x16_bf16 v[80:95], v[156:159], v[112:115], v[80:95]
	v_mfma_f32_32x32x16_bf16 v[64:79], v[160:163], v[112:115], v[64:79]
	ds_read_b128 v[156:159], v250 offset:49152
	ds_read_b128 v[160:163], v250 offset:57344
	v_exp_f32_e32 v238, v165
	s_waitcnt lgkmcnt(0)
	v_mfma_f32_32x32x16_bf16 v[80:95], v[156:159], v[116:119], v[80:95]
	v_mfma_f32_32x32x16_bf16 v[64:79], v[160:163], v[116:119], v[64:79]
	ds_read_b128 v[156:159], v251 offset:49152
	ds_read_b128 v[160:163], v251 offset:57344
	v_exp_f32_e32 v239, v166
	s_waitcnt lgkmcnt(0)
	v_mfma_f32_32x32x16_bf16 v[80:95], v[156:159], v[120:123], v[80:95]
	v_mfma_f32_32x32x16_bf16 v[64:79], v[160:163], v[120:123], v[64:79]
	ds_read_b128 v[156:159], v252 offset:49152
	ds_read_b128 v[160:163], v252 offset:57344
	s_waitcnt lgkmcnt(0)
	v_mfma_f32_32x32x16_bf16 v[80:95], v[156:159], v[124:127], v[80:95]
	v_add_f32_e32 v156, 0, v177
	v_add_f32_e32 v156, v178, v156
	v_add_f32_e32 v156, v179, v156
	v_add_f32_e32 v156, v221, v156
	v_add_f32_e32 v156, v222, v156
	v_add_f32_e32 v156, v223, v156
	v_add_f32_e32 v156, v224, v156
	v_add_f32_e32 v156, v225, v156
	v_add_f32_e32 v156, v226, v156
	v_add_f32_e32 v156, v227, v156
	v_add_f32_e32 v156, v228, v156
	v_add_f32_e32 v156, v229, v156
	v_add_f32_e32 v156, v230, v156
	v_add_f32_e32 v156, v231, v156
	v_add_f32_e32 v156, v232, v156
	v_add_f32_e32 v156, v233, v156
	v_add_f32_e32 v156, v237, v156
	v_add_f32_e32 v156, v238, v156
	v_add_f32_e32 v156, v239, v156
	v_add_f32_e32 v156, v167, v156
	v_add_f32_e32 v156, v168, v156
	v_add_f32_e32 v156, v169, v156
	v_add_f32_e32 v156, v170, v156
	v_add_f32_e32 v156, v171, v156
	v_add_f32_e32 v156, v172, v156
	v_add_f32_e32 v156, v173, v156
	v_mfma_f32_32x32x16_bf16 v[64:79], v[160:163], v[124:127], v[64:79]
	v_add_f32_e32 v156, v174, v156
	v_add_f32_e32 v156, v175, v156
	v_add_f32_e32 v156, v176, v156
	v_add_f32_e32 v156, v234, v156
	v_add_f32_e32 v156, v235, v156
	v_add_f32_e32 v156, v236, v156
	v_mov_b32_e32 v157, v156
	s_nop 1
	v_permlane32_swap_b32_e32 v156, v157
	v_cvt_pk_bf16_f32 v158, v177, v178
	v_cvt_pk_bf16_f32 v159, v179, v221
	v_cvt_pk_bf16_f32 v160, v222, v223
	v_cvt_pk_bf16_f32 v161, v224, v225
	v_cvt_pk_bf16_f32 v162, v226, v227
	v_cvt_pk_bf16_f32 v163, v228, v229
	v_cvt_pk_bf16_f32 v164, v230, v231
	v_cvt_pk_bf16_f32 v165, v232, v233
	v_cvt_pk_bf16_f32 v166, v237, v238
	v_cvt_pk_bf16_f32 v167, v239, v167
	v_cvt_pk_bf16_f32 v168, v168, v169
	v_cvt_pk_bf16_f32 v169, v170, v171
	v_cvt_pk_bf16_f32 v170, v172, v173
	v_cvt_pk_bf16_f32 v171, v174, v175
	v_cvt_pk_bf16_f32 v172, v176, v234
	v_cvt_pk_bf16_f32 v173, v235, v236
	s_nop 0
	v_permlane32_swap_b32_e32 v158, v160
	v_permlane32_swap_b32_e32 v159, v161
	v_permlane32_swap_b32_e32 v162, v164
	v_permlane32_swap_b32_e32 v163, v165
	v_permlane32_swap_b32_e32 v166, v168
	v_permlane32_swap_b32_e32 v167, v169
	v_permlane32_swap_b32_e32 v170, v172
	v_permlane32_swap_b32_e32 v171, v173
	v_add_u32_e32 v178, s73, v192
	ds_read_b64_tr_b16 v[174:175], v178 offset:0
	ds_read_b64_tr_b16 v[176:177], v178 offset:0x800
	ds_read_b64_tr_b16 v[222:223], v178 offset:0x1000
	ds_read_b64_tr_b16 v[224:225], v178 offset:0x1800
	ds_read_b64_tr_b16 v[226:227], v178 offset:0x2000
	ds_read_b64_tr_b16 v[228:229], v178 offset:0x2800
	ds_read_b64_tr_b16 v[230:231], v178 offset:0x3000
	ds_read_b64_tr_b16 v[232:233], v178 offset:0x3800
	s_waitcnt lgkmcnt(4)
; #define SBAR() __builtin_amdgcn_sched_barrier(0)
; #define PV_RD(d0, kh, X) do { constexpr int b_ = v_rd_off(d0, 2 * (kh), 0); TRRD(X##l0, b_); TRRD(X##h0, b_ + 2048); TRRD(X##l1, b_ + 4096); TRRD(X##h1, b_ + 6144); } while (0)
; #define PV_MM(d0, X, PA, PB) do { \
;         o[d0] = __builtin_amdgcn_mfma_f32_32x32x16_bf16(PA, (bf16x8){X##l0[0], X##l0[1], X##l0[2], X##l0[3], X##h0[0], X##h0[1], X##h0[2], X##h0[3]}, o[d0], 0, 0, 0);   \
;         o[d0] = __builtin_amdgcn_mfma_f32_32x32x16_bf16(PB, (bf16x8){X##l1[0], X##l1[1], X##l1[2], X##l1[3], X##h1[0], X##h1[1], X##h1[2], X##h1[3]}, o[d0], 0, 0, 0); } while (0)
; #define PV_W4() do { asm volatile("s_waitcnt lgkmcnt(4)" ::: "memory"); SBAR(); } while (0)
; #define PV_W0() do { asm volatile("s_waitcnt lgkmcnt(0)" ::: "memory"); SBAR(); } while (0)
; __device__ __forceinline__ void mask_tile(f32x16& p0, f32x16& p1, int dq) {
;     const float NEG = -__builtin_inff();
; #pragma unroll
;     for (int r = 0; r < 16; ++r) { const int c = (r & 3) + 8 * (r >> 2); if (dq - c < 0) p0[r] = NEG; if (dq - c - 32 < 0) p1[r] = NEG; }
; }
; __device__ __forceinline__ void pv_tile(f32x16* o, int vb0, bf16x8 pa0, bf16x8 pa1, bf16x8 pa2, bf16x8 pa3) {
;     ...
;     s16x4 al0, al1, ah0, ah1, bl0, bl1, bh0, bh1;
;     PV_RD(0, 0, a);
;     PV_RD(0, 1, b); PV_W4(); PV_MM(0, a, pa0, pa1); SBAR();
;     PV_RD(1, 0, a); PV_W4(); PV_MM(0, b, pa2, pa3); SBAR();
;     PV_RD(1, 1, b); PV_W4(); PV_MM(1, a, pa0, pa1); SBAR();
;     PV_RD(2, 0, a); PV_W4(); PV_MM(1, b, pa2, pa3); SBAR();
;     PV_RD(2, 1, b); PV_W4(); PV_MM(2, a, pa0, pa1); SBAR();
;     PV_RD(3, 0, a); PV_W4(); PV_MM(2, b, pa2, pa3); SBAR();
;     PV_RD(3, 1, b); PV_W4(); PV_MM(3, a, pa0, pa1); SBAR();
;     PV_W0(); PV_MM(3, b, pa2, pa3);
	s_nop 0
	v_mfma_f32_32x32x16_bf16 v[48:63], v[158:161], v[174:177], v[48:63]
	v_mfma_f32_32x32x16_bf16 v[48:63], v[162:165], v[222:225], v[48:63]
	ds_read_b64_tr_b16 v[174:175], v178 offset:0x200
	ds_read_b64_tr_b16 v[176:177], v178 offset:0xa00
	ds_read_b64_tr_b16 v[222:223], v178 offset:0x1200
	ds_read_b64_tr_b16 v[224:225], v178 offset:0x1a00
	s_waitcnt lgkmcnt(4)
	v_mfma_f32_32x32x16_bf16 v[48:63], v[166:169], v[226:229], v[48:63]
	v_mfma_f32_32x32x16_bf16 v[48:63], v[170:173], v[230:233], v[48:63]
	ds_read_b64_tr_b16 v[226:227], v178 offset:0x2200
	ds_read_b64_tr_b16 v[228:229], v178 offset:0x2a00
	ds_read_b64_tr_b16 v[230:231], v178 offset:0x3200
	ds_read_b64_tr_b16 v[232:233], v178 offset:0x3a00
	s_waitcnt lgkmcnt(4)
	v_mfma_f32_32x32x16_bf16 v[32:47], v[158:161], v[174:177], v[32:47]
	v_mfma_f32_32x32x16_bf16 v[32:47], v[162:165], v[222:225], v[32:47]
	ds_read_b64_tr_b16 v[174:175], v178 offset:0x400
	ds_read_b64_tr_b16 v[176:177], v178 offset:0xc00
	ds_read_b64_tr_b16 v[222:223], v178 offset:0x1400
	ds_read_b64_tr_b16 v[224:225], v178 offset:0x1c00
	s_waitcnt lgkmcnt(4)
	v_mfma_f32_32x32x16_bf16 v[32:47], v[166:169], v[226:229], v[32:47]
	v_mfma_f32_32x32x16_bf16 v[32:47], v[170:173], v[230:233], v[32:47]
	ds_read_b64_tr_b16 v[226:227], v178 offset:0x2400
	ds_read_b64_tr_b16 v[228:229], v178 offset:0x2c00
	ds_read_b64_tr_b16 v[230:231], v178 offset:0x3400
	ds_read_b64_tr_b16 v[232:233], v178 offset:0x3c00
	s_waitcnt lgkmcnt(4)
	v_mfma_f32_32x32x16_bf16 v[16:31], v[158:161], v[174:177], v[16:31]
	v_mfma_f32_32x32x16_bf16 v[16:31], v[162:165], v[222:225], v[16:31]
	ds_read_b64_tr_b16 v[174:175], v178 offset:0x600
	ds_read_b64_tr_b16 v[176:177], v178 offset:0xe00
	ds_read_b64_tr_b16 v[222:223], v178 offset:0x1600
	ds_read_b64_tr_b16 v[224:225], v178 offset:0x1e00
	s_waitcnt lgkmcnt(4)
	v_mfma_f32_32x32x16_bf16 v[16:31], v[166:169], v[226:229], v[16:31]
	v_mfma_f32_32x32x16_bf16 v[16:31], v[170:173], v[230:233], v[16:31]
	ds_read_b64_tr_b16 v[226:227], v178 offset:0x2600
	ds_read_b64_tr_b16 v[228:229], v178 offset:0x2e00
	ds_read_b64_tr_b16 v[230:231], v178 offset:0x3600
	ds_read_b64_tr_b16 v[232:233], v178 offset:0x3e00
	s_waitcnt lgkmcnt(4)
	v_mfma_f32_32x32x16_bf16 v[0:15], v[158:161], v[174:177], v[0:15]
	v_mfma_f32_32x32x16_bf16 v[0:15], v[162:165], v[222:225], v[0:15]
	s_waitcnt lgkmcnt(0)
	v_mfma_f32_32x32x16_bf16 v[0:15], v[166:169], v[226:229], v[0:15]
	s_cmp_le_i32 s92, s91
	v_mfma_f32_32x32x16_bf16 v[0:15], v[170:173], v[230:233], v[0:15]
	s_cbranch_scc1 .LBB0_539
	v_subrev_u32_e32 v158, 64, v216
	v_cmp_gt_i32_e64 s[62:63], 26, v158
	v_cmp_gt_i32_e64 s[64:65], 27, v158
	v_cmp_gt_i32_e64 s[60:61], 25, v158
	s_and_b64 s[62:63], s[64:65], s[62:63]
	v_cmp_gt_i32_e64 s[58:59], 24, v158
	s_and_b64 s[60:61], s[62:63], s[60:61]
	v_cmp_gt_i32_e64 s[56:57], 19, v158
	s_and_b64 s[58:59], s[60:61], s[58:59]
	v_cmp_gt_i32_e64 s[54:55], 18, v158
	s_and_b64 s[56:57], s[58:59], s[56:57]
	v_cmp_gt_i32_e64 s[52:53], 17, v158
	s_and_b64 s[54:55], s[56:57], s[54:55]
	v_cmp_gt_i32_e64 s[50:51], 16, v158
	s_and_b64 s[52:53], s[54:55], s[52:53]
	v_cmp_gt_i32_e64 s[48:49], 11, v158
	s_and_b64 s[50:51], s[52:53], s[50:51]
	v_cmp_gt_i32_e64 s[46:47], 10, v158
	s_and_b64 s[48:49], s[50:51], s[48:49]
	v_cmp_gt_i32_e64 s[44:45], 9, v158
	s_and_b64 s[46:47], s[48:49], s[46:47]
	v_cmp_gt_i32_e64 s[42:43], 8, v158
	s_and_b64 s[44:45], s[46:47], s[44:45]
	v_cmp_gt_i32_e64 s[40:41], 3, v158
	s_and_b64 s[42:43], s[44:45], s[42:43]
	v_cmp_gt_i32_e64 s[38:39], 2, v158
	s_and_b64 s[40:41], s[42:43], s[40:41]
	v_cmp_gt_i32_e64 s[36:37], 1, v158
	s_and_b64 s[38:39], s[40:41], s[38:39]
	v_cmp_gt_i32_e64 s[34:35], 0, v158
	s_and_b64 s[36:37], s[38:39], s[36:37]
	s_and_b64 s[34:35], s[36:37], s[34:35]
	v_cmp_gt_i32_e64 s[28:29], 58, v158
	v_cndmask_b32_e64 v80, v80, v130, s[34:35]
	v_cmp_gt_i32_e64 s[34:35], 59, v158
	v_cmp_gt_i32_e64 s[26:27], 57, v158
	s_and_b64 s[28:29], s[34:35], s[28:29]
	v_cmp_gt_i32_e64 s[24:25], 56, v158
	s_and_b64 s[26:27], s[28:29], s[26:27]
	v_cmp_gt_i32_e64 s[22:23], 51, v158
	s_and_b64 s[24:25], s[26:27], s[24:25]
	v_cmp_gt_i32_e64 s[20:21], 50, v158
	s_and_b64 s[22:23], s[24:25], s[22:23]
	v_cmp_gt_i32_e64 s[18:19], 49, v158
	s_and_b64 s[20:21], s[22:23], s[20:21]
	v_cmp_gt_i32_e64 s[16:17], 48, v158
	s_and_b64 s[18:19], s[20:21], s[18:19]
	v_cmp_gt_i32_e64 s[14:15], 43, v158
	s_and_b64 s[16:17], s[18:19], s[16:17]
	v_cmp_gt_i32_e64 s[12:13], 42, v158
	s_and_b64 s[14:15], s[16:17], s[14:15]
	v_cmp_gt_i32_e64 s[10:11], 41, v158
	s_and_b64 s[12:13], s[14:15], s[12:13]
	v_cmp_gt_i32_e64 s[8:9], 40, v158
	s_and_b64 s[10:11], s[12:13], s[10:11]
	v_cmp_gt_i32_e64 s[6:7], 35, v158
	s_and_b64 s[8:9], s[10:11], s[8:9]
	v_cmp_gt_i32_e64 s[4:5], 34, v158
	s_and_b64 s[6:7], s[8:9], s[6:7]
	v_cmp_gt_i32_e64 s[2:3], 33, v158
	s_and_b64 s[4:5], s[6:7], s[4:5]
	v_cmp_gt_i32_e32 vcc, 32, v158
	s_and_b64 s[2:3], s[4:5], s[2:3]
	s_and_b64 vcc, s[2:3], vcc
	v_cndmask_b32_e64 v95, v95, v130, s[64:65]
	v_cndmask_b32_e64 v94, v94, v130, s[62:63]
	v_cndmask_b32_e64 v93, v93, v130, s[60:61]
	v_cndmask_b32_e64 v92, v92, v130, s[58:59]
	v_cndmask_b32_e64 v91, v91, v130, s[56:57]
	v_cndmask_b32_e64 v90, v90, v130, s[54:55]
	v_cndmask_b32_e64 v89, v89, v130, s[52:53]
	v_cndmask_b32_e64 v88, v88, v130, s[50:51]
	v_cndmask_b32_e64 v87, v87, v130, s[48:49]
	v_cndmask_b32_e64 v86, v86, v130, s[46:47]
	v_cndmask_b32_e64 v85, v85, v130, s[44:45]
	v_cndmask_b32_e64 v84, v84, v130, s[42:43]
	v_cndmask_b32_e64 v83, v83, v130, s[40:41]
	v_cndmask_b32_e64 v82, v82, v130, s[38:39]
	v_cndmask_b32_e64 v81, v81, v130, s[36:37]
	v_cndmask_b32_e64 v79, v79, v130, s[34:35]
	v_cndmask_b32_e64 v78, v78, v130, s[28:29]
	v_cndmask_b32_e64 v77, v77, v130, s[26:27]
	v_cndmask_b32_e64 v76, v76, v130, s[24:25]
	v_cndmask_b32_e64 v75, v75, v130, s[22:23]
	v_cndmask_b32_e64 v74, v74, v130, s[20:21]
	v_cndmask_b32_e64 v73, v73, v130, s[18:19]
	v_cndmask_b32_e64 v72, v72, v130, s[16:17]
	v_cndmask_b32_e64 v71, v71, v130, s[14:15]
	v_cndmask_b32_e64 v70, v70, v130, s[12:13]
	v_cndmask_b32_e64 v69, v69, v130, s[10:11]
	v_cndmask_b32_e64 v68, v68, v130, s[8:9]
	v_cndmask_b32_e64 v67, v67, v130, s[6:7]
	v_cndmask_b32_e64 v66, v66, v130, s[4:5]
	v_cndmask_b32_e64 v65, v65, v130, s[2:3]
	v_cndmask_b32_e32 v64, v64, v130, vcc

; #define SBAR() __builtin_amdgcn_sched_barrier(0)
; #define PV_RD(d0, kh, X) do { constexpr int b_ = v_rd_off(d0, 2 * (kh), 0); TRRD(X##l0, b_); TRRD(X##h0, b_ + 2048); TRRD(X##l1, b_ + 4096); TRRD(X##h1, b_ + 6144); } while (0)
; #define PV_MM(d0, X, PA, PB) do { \
;         o[d0] = __builtin_amdgcn_mfma_f32_32x32x16_bf16(PA, (bf16x8){X##l0[0], X##l0[1], X##l0[2], X##l0[3], X##h0[0], X##h0[1], X##h0[2], X##h0[3]}, o[d0], 0, 0, 0);   \
;         o[d0] = __builtin_amdgcn_mfma_f32_32x32x16_bf16(PB, (bf16x8){X##l1[0], X##l1[1], X##l1[2], X##l1[3], X##h1[0], X##h1[1], X##h1[2], X##h1[3]}, o[d0], 0, 0, 0); } while (0)
; #define PV_W4() do { asm volatile("s_waitcnt lgkmcnt(4)" ::: "memory"); SBAR(); } while (0)
; #define PV_W0() do { asm volatile("s_waitcnt lgkmcnt(0)" ::: "memory"); SBAR(); } while (0)
; __device__ __forceinline__ void finishSM(f32x16& p0, f32x16& p1, float alpha, float& l_reg, bf16x8& pa0, bf16x8& pa1, bf16x8& pa2, bf16x8& pa3) {
; #pragma unroll
;     for (int r = 0; r < 16; ++r) p1[r] = __builtin_amdgcn_exp2f(p1[r]);
;     float ps = 0;
; #pragma unroll
;     for (int r = 0; r < 16; ++r) ps += p0[r];
; #pragma unroll
;     for (int r = 0; r < 16; ++r) ps += p1[r];
;     { auto rr = __builtin_amdgcn_permlane32_swap(__float_as_uint(ps), __float_as_uint(ps), false, false);
;       ps = __uint_as_float(rr[0]) + __uint_as_float(rr[1]); }
;     l_reg = l_reg * alpha + ps;
;     ...
;     PK4(p0, 0, pa0); PK4(p0, 8, pa1); PK4(p1, 0, pa2); PK4(p1, 8, pa3);
; __device__ __forceinline__ void pv_tile(f32x16* o, int vb0, bf16x8 pa0, bf16x8 pa1, bf16x8 pa2, bf16x8 pa3) {
;     ...
;     s16x4 al0, al1, ah0, ah1, bl0, bl1, bh0, bh1;
;     PV_RD(0, 0, a);
;     PV_RD(0, 1, b); PV_W4(); PV_MM(0, a, pa0, pa1); SBAR();
;     PV_RD(1, 0, a); PV_W4(); PV_MM(0, b, pa2, pa3); SBAR();
;     PV_RD(1, 1, b); PV_W4(); PV_MM(1, a, pa0, pa1); SBAR();
;     PV_RD(2, 0, a); PV_W4(); PV_MM(1, b, pa2, pa3); SBAR();
;     PV_RD(2, 1, b); PV_W4(); PV_MM(2, a, pa0, pa1); SBAR();
;     PV_RD(3, 0, a); PV_W4(); PV_MM(2, b, pa2, pa3); SBAR();
;     PV_RD(3, 1, b); PV_W4(); PV_MM(3, a, pa0, pa1); SBAR();
;     PV_W0(); PV_MM(3, b, pa2, pa3);
.LBB0_553:
	v_add_f32_e32 v64, 0, v221
	v_add_f32_e32 v64, v236, v64
	v_add_f32_e32 v64, v233, v64
	v_add_f32_e32 v64, v235, v64
	v_add_f32_e32 v64, v231, v64
	v_add_f32_e32 v64, v234, v64
	v_add_f32_e32 v64, v230, v64
	v_add_f32_e32 v64, v232, v64
	v_add_f32_e32 v64, v227, v64
	v_add_f32_e32 v64, v229, v64
	v_add_f32_e32 v64, v225, v64
	v_add_f32_e32 v64, v228, v64
	v_exp_f32_e32 v74, v168
	v_add_f32_e32 v64, v223, v64
	v_exp_f32_e32 v75, v169
	v_add_f32_e32 v64, v226, v64
	v_exp_f32_e32 v76, v172
	v_add_f32_e32 v64, v222, v64
	v_exp_f32_e32 v77, v173
	v_add_f32_e32 v64, v224, v64
	v_exp_f32_e32 v78, v176
	v_add_f32_e32 v64, v74, v64
	v_exp_f32_e32 v79, v177
	v_add_f32_e32 v64, v75, v64
	v_exp_f32_e32 v80, v166
	v_add_f32_e32 v64, v76, v64
	v_exp_f32_e32 v81, v167
	v_add_f32_e32 v64, v77, v64
	v_exp_f32_e32 v82, v170
	v_add_f32_e32 v64, v78, v64
	v_exp_f32_e32 v83, v171
	v_add_f32_e32 v64, v79, v64
	v_exp_f32_e32 v84, v174
	v_add_f32_e32 v64, v80, v64
	v_exp_f32_e32 v85, v175
	v_add_f32_e32 v64, v81, v64
	v_exp_f32_e32 v86, v178
	v_add_f32_e32 v64, v82, v64
	v_exp_f32_e32 v87, v179
	v_add_f32_e32 v64, v83, v64
	v_readlane_b32 s7, v247, 12
	v_readlane_b32 s2, v247, 13
	v_exp_f32_e32 v88, v164
	v_add_f32_e32 v64, v84, v64
	s_or_b32 s2, s7, s2
	v_exp_f32_e32 v89, v165
	v_add_f32_e32 v64, v85, v64
	s_ashr_i32 s3, s2, 31
	v_readlane_b32 s4, v248, 63
	v_add_f32_e32 v64, v86, v64
	s_lshl_b64 s[2:3], s[2:3], 11
	v_readlane_b32 s5, v247, 0
	v_add_f32_e32 v64, v87, v64
	s_or_b64 s[2:3], s[2:3], s[4:5]
	v_add_f32_e32 v64, v88, v64
	s_lshl_b64 s[68:69], s[2:3], 1
	v_readlane_b32 s93, v247, 10
	v_add_f32_e32 v64, v89, v64
	s_add_u32 s2, s93, s68
	v_readlane_b32 s3, v248, 37
	v_mov_b32_e32 v65, v64
	s_addc_u32 s3, s3, s69
	s_nop 0
	v_permlane32_swap_b32_e32 v64, v65
	v_cvt_pk_bf16_f32 v66, v221, v236
	v_cvt_pk_bf16_f32 v67, v233, v235
	v_cvt_pk_bf16_f32 v68, v231, v234
	v_cvt_pk_bf16_f32 v69, v230, v232
	v_cvt_pk_bf16_f32 v70, v227, v229
	v_cvt_pk_bf16_f32 v71, v225, v228
	v_cvt_pk_bf16_f32 v72, v223, v226
	v_cvt_pk_bf16_f32 v73, v222, v224
	v_cvt_pk_bf16_f32 v74, v74, v75
	v_cvt_pk_bf16_f32 v75, v76, v77
	v_cvt_pk_bf16_f32 v76, v78, v79
	v_cvt_pk_bf16_f32 v77, v80, v81
	v_cvt_pk_bf16_f32 v78, v82, v83
	v_cvt_pk_bf16_f32 v79, v84, v85
	v_cvt_pk_bf16_f32 v80, v86, v87
	v_cvt_pk_bf16_f32 v81, v88, v89
	s_nop 0
	v_permlane32_swap_b32_e32 v66, v68
	v_permlane32_swap_b32_e32 v67, v69
	v_permlane32_swap_b32_e32 v70, v72
	v_permlane32_swap_b32_e32 v71, v73
	v_permlane32_swap_b32_e32 v74, v76
	v_permlane32_swap_b32_e32 v75, v77
	v_permlane32_swap_b32_e32 v78, v80
	v_permlane32_swap_b32_e32 v79, v81
	v_add_u32_e32 v98, s76, v192
	ds_read_b64_tr_b16 v[82:83], v98 offset:0
	ds_read_b64_tr_b16 v[84:85], v98 offset:0x800
	ds_read_b64_tr_b16 v[86:87], v98 offset:0x1000
	ds_read_b64_tr_b16 v[88:89], v98 offset:0x1800
	ds_read_b64_tr_b16 v[90:91], v98 offset:0x2000
	ds_read_b64_tr_b16 v[92:93], v98 offset:0x2800
	ds_read_b64_tr_b16 v[94:95], v98 offset:0x3000
	ds_read_b64_tr_b16 v[96:97], v98 offset:0x3800
	s_waitcnt lgkmcnt(4)
	s_nop 0
	v_mfma_f32_32x32x16_bf16 v[48:63], v[66:69], v[82:85], v[48:63]
	v_mfma_f32_32x32x16_bf16 v[48:63], v[70:73], v[86:89], v[48:63]
	ds_read_b64_tr_b16 v[82:83], v98 offset:0x200
	ds_read_b64_tr_b16 v[84:85], v98 offset:0xa00
	ds_read_b64_tr_b16 v[86:87], v98 offset:0x1200
	ds_read_b64_tr_b16 v[88:89], v98 offset:0x1a00
	s_waitcnt lgkmcnt(4)
	v_mfma_f32_32x32x16_bf16 v[48:63], v[74:77], v[90:93], v[48:63]
	v_mfma_f32_32x32x16_bf16 v[48:63], v[78:81], v[94:97], v[48:63]
	ds_read_b64_tr_b16 v[90:91], v98 offset:0x2200
	ds_read_b64_tr_b16 v[92:93], v98 offset:0x2a00
	ds_read_b64_tr_b16 v[94:95], v98 offset:0x3200
	ds_read_b64_tr_b16 v[96:97], v98 offset:0x3a00
	s_waitcnt lgkmcnt(4)
	v_mfma_f32_32x32x16_bf16 v[32:47], v[66:69], v[82:85], v[32:47]
	v_mfma_f32_32x32x16_bf16 v[32:47], v[70:73], v[86:89], v[32:47]
	ds_read_b64_tr_b16 v[82:83], v98 offset:0x400
	ds_read_b64_tr_b16 v[84:85], v98 offset:0xc00
	ds_read_b64_tr_b16 v[86:87], v98 offset:0x1400
	ds_read_b64_tr_b16 v[88:89], v98 offset:0x1c00
	s_waitcnt lgkmcnt(4)
	v_mfma_f32_32x32x16_bf16 v[32:47], v[74:77], v[90:93], v[32:47]
	v_mfma_f32_32x32x16_bf16 v[32:47], v[78:81], v[94:97], v[32:47]
	ds_read_b64_tr_b16 v[90:91], v98 offset:0x2400
	ds_read_b64_tr_b16 v[92:93], v98 offset:0x2c00
	ds_read_b64_tr_b16 v[94:95], v98 offset:0x3400
	ds_read_b64_tr_b16 v[96:97], v98 offset:0x3c00
	s_waitcnt lgkmcnt(4)
	v_mfma_f32_32x32x16_bf16 v[16:31], v[66:69], v[82:85], v[16:31]
	v_mfma_f32_32x32x16_bf16 v[16:31], v[70:73], v[86:89], v[16:31]
	ds_read_b64_tr_b16 v[82:83], v98 offset:0x600
	ds_read_b64_tr_b16 v[84:85], v98 offset:0xe00
	ds_read_b64_tr_b16 v[86:87], v98 offset:0x1600
	ds_read_b64_tr_b16 v[88:89], v98 offset:0x1e00
	s_waitcnt lgkmcnt(4)
	v_mfma_f32_32x32x16_bf16 v[16:31], v[74:77], v[90:93], v[16:31]
	v_mfma_f32_32x32x16_bf16 v[16:31], v[78:81], v[94:97], v[16:31]
	ds_read_b64_tr_b16 v[90:91], v98 offset:0x2600
	ds_read_b64_tr_b16 v[92:93], v98 offset:0x2e00
	ds_read_b64_tr_b16 v[94:95], v98 offset:0x3600
	ds_read_b64_tr_b16 v[96:97], v98 offset:0x3e00
	s_waitcnt lgkmcnt(4)
	v_mfma_f32_32x32x16_bf16 v[0:15], v[66:69], v[82:85], v[0:15]
	v_mfma_f32_32x32x16_bf16 v[0:15], v[70:73], v[86:89], v[0:15]
	s_waitcnt lgkmcnt(0)
	v_mfma_f32_32x32x16_bf16 v[0:15], v[74:77], v[90:93], v[0:15]
	v_mfma_f32_32x32x16_bf16 v[0:15], v[78:81], v[94:97], v[0:15]
	v_lshl_add_u64 v[66:67], s[2:3], 0, v[132:133]
	v_mov_b32_e32 v147, v129
	s_waitcnt vmcnt(0) lgkmcnt(0)
	s_barrier
; #define LAS __attribute__((address_space(3)))
; __device__ __forceinline__ unsigned cvt_pk_bf16(float lo, float hi) { unsigned r; asm volatile("v_cvt_pk_bf16_f32 %0, %1, %2" : "=v"(r) : "v"(lo), "v"(hi)); return r; }
; __device__ __forceinline__ float bf_lo(unsigned w) { return __uint_as_float(w << 16); }
; __device__ __forceinline__ float bf_hi(unsigned w) { return __uint_as_float(w & 0xffff0000u); }
; __device__ __forceinline__ void fox_block(const BlockRef& cur, const BlockRef& nxt, char* lds, Seam& S, const int tid) {
;     ...
;     { const bf16_t* Kh = nxt.K; const bf16_t* Vh = nxt.V;
; #pragma unroll
;       for (int d0 = 0; d0 < 8; ++d0) S.qr[d0] = load8(nxt.Q + (size_t)(wid * QBLK + r32) * LD + d0 * 16 + hi * 8);
;       SBAR(); DMA_K(0, 0); DMA_K(1, SLOT); DMA_V(0, 0); SBAR(); }
;     if (hi == 0) li_l[r32] = l_reg; asm volatile("s_waitcnt lgkmcnt(0)" ::: "memory");
;     float rli[16];
; #pragma unroll
;     for (int r = 0; r < 16; ++r) rli[r] = __builtin_amdgcn_rcpf(li_l[crow(r, hi)]);
;     typedef __attribute__((address_space(1))) bf16_t gbf16; typedef __attribute__((address_space(1))) u32x4 gu32x4;
;     LAS float* stg = (LAS float*)(lds3 + SLOT + wid * 4096);
;     const int er = lane >> 2, eq = lane & 3;
;     gbf16* obase = (gbf16*)(cur.O + (size_t)(wid * QBLK + er) * LD + 8 * eq); const gbf16* zbase = (const gbf16*)(cur.Z + (size_t)(wid * QBLK + er) * LD + 8 * eq);
; #pragma unroll
;     for (int d0 = 0; d0 < 4; ++d0) {
; #pragma unroll
;         for (int r = 0; r < 16; ++r) stg[crow(r, hi) * 32 + r32] = o[d0][r] * rli[r];
;         asm volatile("s_waitcnt lgkmcnt(0)" ::: "memory");
;         gbf16* op = obase; const gbf16* zp = zbase;
; #pragma unroll
;         for (int i = 0; i < 2; ++i) {
;             asm volatile("" : "+v"(op), "+v"(zp));
;             const f32x4 v0 = *(const LAS f32x4*)(stg + (er + 16 * i) * 32 + 8 * eq), v1 = *(const LAS f32x4*)(stg + (er + 16 * i) * 32 + 8 * eq + 4);
;             const u32x4 z = __builtin_nontemporal_load((const gu32x4*)(zp + d0 * 32));
;             u32x4 w; w.x = cvt_pk_bf16(v0.x * bf_lo(z.x), v0.y * bf_hi(z.x)); w.y = cvt_pk_bf16(v0.z * bf_lo(z.y), v0.w * bf_hi(z.y));
;             w.z = cvt_pk_bf16(v1.x * bf_lo(z.z), v1.y * bf_hi(z.z)); w.w = cvt_pk_bf16(v1.z * bf_lo(z.w), v1.w * bf_hi(z.w));
;             *(gu32x4*)(op + d0 * 32) = w;
;             op += 16 * LD; zp += 16 * LD; }
	v_lshl_add_u64 v[66:67], v[66:67], 0, v[146:147]
	global_load_dwordx4 v[96:99], v[66:67], off
	global_load_dwordx4 v[100:103], v[66:67], off offset:32
	global_load_dwordx4 v[104:107], v[66:67], off offset:64
	global_load_dwordx4 v[108:111], v[66:67], off offset:96
	global_load_dwordx4 v[112:115], v[66:67], off offset:128
	global_load_dwordx4 v[116:119], v[66:67], off offset:160
	global_load_dwordx4 v[120:123], v[66:67], off offset:192
	global_load_dwordx4 v[124:127], v[66:67], off offset:224
	v_readlane_b32 s2, v247, 15
	s_mov_b32 m0, s2
	v_readlane_b32 s2, v247, 16
	global_load_lds_dwordx4 v[144:145], off
	s_mov_b32 m0, s2
	v_readlane_b32 s2, v247, 17
	global_load_lds_dwordx4 v[142:143], off
	s_mov_b32 m0, s2
	v_readlane_b32 s2, v247, 18
	global_load_lds_dwordx4 v[136:137], off
	s_mov_b32 m0, s2
	v_readlane_b32 s2, v247, 19
	global_load_lds_dwordx4 v[138:139], off
	s_mov_b32 m0, s70
	s_nop 0
	global_load_lds_dwordx4 v[140:141], off
	s_mov_b32 m0, s2
	s_nop 0
	global_load_lds_dwordx4 v[134:135], off
	s_and_saveexec_b64 s[2:3], s[0:1]
	v_add_f32_e32 v64, v64, v65
	v_fmac_f32_e32 v64, v215, v158
	ds_write_b32 v214, v64
	s_or_b64 exec, exec, s[2:3]
	s_waitcnt lgkmcnt(0)
	ds_read_b128 v[64:67], v131
	ds_read_b128 v[68:71], v131 offset:32
	v_readlane_b32 s2, v248, 42
	s_add_u32 s2, s2, s78
	v_readlane_b32 s3, v248, 43
	s_waitcnt lgkmcnt(0)
	v_rcp_f32_e32 v72, v64
	v_rcp_f32_e32 v73, v65
	v_rcp_f32_e32 v74, v66
	v_rcp_f32_e32 v75, v67
	v_rcp_f32_e32 v76, v68
	ds_read_b128 v[64:67], v131 offset:64
	v_rcp_f32_e32 v77, v69
	v_rcp_f32_e32 v78, v70
	v_rcp_f32_e32 v79, v71
	ds_read_b128 v[68:71], v131 offset:96
	s_addc_u32 s3, s3, s79
	v_readlane_b32 s4, v248, 54
	s_add_u32 s4, s4, s78
	v_readlane_b32 s5, v248, 56
	v_readlane_b32 s6, v247, 14
	s_addc_u32 s5, s5, s79
	s_lshl_b32 s6, s6, 12
	s_waitcnt lgkmcnt(0)
	v_rcp_f32_e32 v84, v68
	s_add_i32 s6, s6, 0
	v_lshlrev_b32_e32 v68, 3, v155
	v_lshlrev_b32_e32 v133, 2, v199
	v_lshlrev_b32_e32 v170, 9, v213
	v_and_b32_e32 v132, 24, v68
	v_add3_u32 v68, s6, v133, v170
	v_rcp_f32_e32 v80, v64
	v_rcp_f32_e32 v81, v65
	v_mul_f32_e32 v48, v48, v72
	v_mul_f32_e32 v49, v49, v73
	v_add_u32_e32 v86, 0x4000, v68
	v_rcp_f32_e32 v82, v66
	v_rcp_f32_e32 v83, v67
	ds_write2_b32 v86, v48, v49 offset1:32
	v_mul_f32_e32 v48, v50, v74
	v_mul_f32_e32 v49, v51, v75
	v_rcp_f32_e32 v85, v69
	ds_write2_b32 v86, v48, v49 offset0:64 offset1:96
	v_mul_f32_e32 v48, v52, v76
	v_mul_f32_e32 v49, v53, v77
	v_add_u32_e32 v87, 0x4400, v68
	v_rcp_f32_e32 v70, v70
	v_rcp_f32_e32 v71, v71
	v_or_b32_e32 v64, s77, v191
	ds_write2_b32 v87, v48, v49 offset1:32
	v_mul_f32_e32 v48, v54, v78
	v_mul_f32_e32 v49, v55, v79
	v_ashrrev_i32_e32 v65, 31, v64
	ds_write2_b32 v87, v48, v49 offset0:64 offset1:96
	v_mul_f32_e32 v48, v56, v80
	v_mul_f32_e32 v49, v57, v81
	v_add_u32_e32 v88, 0x4800, v68
	v_lshlrev_b64 v[66:67], 12, v[64:65]
	ds_write2_b32 v88, v48, v49 offset1:32
	v_mul_f32_e32 v48, v58, v82
	v_mul_f32_e32 v49, v59, v83
	v_lshl_add_u64 v[64:65], s[4:5], 0, v[66:67]
	v_lshlrev_b32_e32 v128, 1, v132
	v_lshl_add_u64 v[66:67], s[2:3], 0, v[66:67]
	ds_write2_b32 v88, v48, v49 offset0:64 offset1:96
	v_mul_f32_e32 v48, v60, v84
	v_mul_f32_e32 v49, v61, v85
	v_add_u32_e32 v89, 0x4c00, v68
	v_lshl_add_u64 v[64:65], v[64:65], 0, v[128:129]
	v_lshl_add_u64 v[66:67], v[66:67], 0, v[128:129]
	ds_write2_b32 v89, v48, v49 offset1:32
	v_mul_f32_e32 v48, v62, v70
	v_mul_f32_e32 v49, v63, v71
	ds_write2_b32 v89, v48, v49 offset0:64 offset1:96
	v_mov_b64_e32 v[62:63], v[64:65]
	v_mov_b64_e32 v[68:69], v[66:67]
	s_waitcnt lgkmcnt(0)
	global_load_dwordx4 v[50:53], v[68:69], off nt
	v_add_co_u32_e32 v250, vcc, 0x10000, v68
	s_nop 1
	v_addc_co_u32_e32 v251, vcc, 0, v69, vcc
	global_load_dwordx4 v[222:225], v[250:251], off nt
	global_load_dwordx4 v[226:229], v[68:69], off offset:64 nt
	global_load_dwordx4 v[230:233], v[250:251], off offset:64 nt
	global_load_dwordx4 v[234:237], v[68:69], off offset:128 nt
	global_load_dwordx4 v[238:241], v[250:251], off offset:128 nt
	global_load_dwordx4 v[242:245], v[68:69], off offset:192 nt
	v_lshlrev_b32_e32 v145, 7, v191
	v_lshlrev_b32_e32 v48, 2, v132
	v_add3_u32 v48, s6, v48, v145
	ds_read_b128 v[54:57], v48 offset:16384
	ds_read_b128 v[58:61], v48 offset:16400
	s_mov_b64 s[2:3], 0x10000
	v_mul_f32_e32 v40, v40, v80
	v_mul_f32_e32 v41, v41, v81
	v_mul_f32_e32 v42, v42, v82
	v_mul_f32_e32 v43, v43, v83
	v_mul_f32_e32 v44, v44, v84
	v_mul_f32_e32 v45, v45, v85
	v_mul_f32_e32 v46, v46, v70
	v_mul_f32_e32 v47, v47, v71
	v_mul_f32_e32 v24, v24, v80
	v_mul_f32_e32 v25, v25, v81
	v_mul_f32_e32 v26, v26, v82
	v_mul_f32_e32 v27, v27, v83
	v_mul_f32_e32 v28, v28, v84
	v_mul_f32_e32 v29, v29, v85
	v_mul_f32_e32 v30, v30, v70
	v_mul_f32_e32 v31, v31, v71
	v_mul_f32_e32 v8, v8, v80
	v_mul_f32_e32 v9, v9, v81
	v_mul_f32_e32 v10, v10, v82
	v_mul_f32_e32 v11, v11, v83
	v_mul_f32_e32 v12, v12, v84
	v_mul_f32_e32 v13, v13, v85
	v_mul_f32_e32 v14, v14, v70
	v_mul_f32_e32 v15, v15, v71
	s_movk_i32 s6, 0x60
	s_or_b32 s4, s7, 64
	s_mov_b32 s87, 4
	s_lshr_b32 s89, s4, 6
	s_waitcnt vmcnt(6)
	v_lshlrev_b32_e32 v49, 16, v50
	v_and_b32_e32 v50, 0xffff0000, v50
	v_lshlrev_b32_e32 v90, 16, v51
	v_and_b32_e32 v51, 0xffff0000, v51
	v_lshlrev_b32_e32 v91, 16, v52
	v_and_b32_e32 v52, 0xffff0000, v52
	s_waitcnt lgkmcnt(1)
	v_mul_f32_e32 v50, v55, v50
	v_mul_f32_e32 v51, v57, v51
	v_lshlrev_b32_e32 v92, 16, v53
	v_and_b32_e32 v53, 0xffff0000, v53
	v_mul_f32_e32 v49, v54, v49
	v_mul_f32_e32 v54, v56, v90
	s_waitcnt lgkmcnt(0)
; #define LAS __attribute__((address_space(3)))
; __device__ __forceinline__ unsigned cvt_pk_bf16(float lo, float hi) { unsigned r; asm volatile("v_cvt_pk_bf16_f32 %0, %1, %2" : "=v"(r) : "v"(lo), "v"(hi)); return r; }
; __device__ __forceinline__ float bf_lo(unsigned w) { return __uint_as_float(w << 16); }
; __device__ __forceinline__ float bf_hi(unsigned w) { return __uint_as_float(w & 0xffff0000u); }
; __device__ __forceinline__ int crow(int r, int hi) { return (r & 3) + 8 * (r >> 2) + 4 * hi; }
; __device__ __forceinline__ void fox_block(const BlockRef& cur, const BlockRef& nxt, char* lds, Seam& S, const int tid) {
;     ...
; #pragma unroll
;     for (int d0 = 0; d0 < 4; ++d0) {
; #pragma unroll
;         for (int r = 0; r < 16; ++r) stg[crow(r, hi) * 32 + r32] = o[d0][r] * rli[r];
;         asm volatile("s_waitcnt lgkmcnt(0)" ::: "memory");
;         gbf16* op = obase; const gbf16* zp = zbase;
; #pragma unroll
;         for (int i = 0; i < 2; ++i) {
;             asm volatile("" : "+v"(op), "+v"(zp));
;             const f32x4 v0 = *(const LAS f32x4*)(stg + (er + 16 * i) * 32 + 8 * eq), v1 = *(const LAS f32x4*)(stg + (er + 16 * i) * 32 + 8 * eq + 4);
;             const u32x4 z = __builtin_nontemporal_load((const gu32x4*)(zp + d0 * 32));
;             u32x4 w; w.x = cvt_pk_bf16(v0.x * bf_lo(z.x), v0.y * bf_hi(z.x)); w.y = cvt_pk_bf16(v0.z * bf_lo(z.y), v0.w * bf_hi(z.y));
;             w.z = cvt_pk_bf16(v1.x * bf_lo(z.z), v1.y * bf_hi(z.z)); w.w = cvt_pk_bf16(v1.z * bf_lo(z.w), v1.w * bf_hi(z.w));
;             *(gu32x4*)(op + d0 * 32) = w;
;             op += 16 * LD; zp += 16 * LD; }
;         asm volatile("s_waitcnt lgkmcnt(0)" ::: "memory"); }
	v_mul_f32_e32 v55, v58, v91
	v_mul_f32_e32 v52, v59, v52
	v_cvt_pk_bf16_f32 v50, v49, v50
	v_cvt_pk_bf16_f32 v51, v54, v51
	v_mul_f32_e32 v56, v60, v92
	v_cvt_pk_bf16_f32 v52, v55, v52
	v_mul_f32_e32 v49, v61, v53
	v_cvt_pk_bf16_f32 v53, v56, v49
	global_store_dwordx4 v[62:63], v[50:53], off
	v_lshl_add_u64 v[54:55], v[62:63], 0, s[2:3]
	v_mul_f32_e32 v49, v32, v72
	v_lshl_add_u64 v[50:51], v[68:69], 0, s[2:3]
	v_mul_f32_e32 v60, v33, v73
	v_mul_f32_e32 v61, v34, v74
	v_mul_f32_e32 v62, v35, v75
	v_mul_f32_e32 v63, v36, v76
	v_mul_f32_e32 v68, v37, v77
	v_mul_f32_e32 v69, v38, v78
	v_mul_f32_e32 v90, v39, v79
	ds_read_b128 v[32:35], v48 offset:18432
	ds_read_b128 v[36:39], v48 offset:18448
	v_mov_b64_e32 v[56:57], v[66:67]
	v_mov_b64_e32 v[58:59], v[64:65]
	s_waitcnt vmcnt(6)
	v_mov_b32_e32 v50, v222
	v_mov_b32_e32 v51, v223
	v_mov_b32_e32 v52, v224
	v_mov_b32_e32 v53, v225
	v_lshlrev_b32_e32 v91, 16, v50
	v_and_b32_e32 v50, 0xffff0000, v50
	v_lshlrev_b32_e32 v92, 16, v51
	v_and_b32_e32 v51, 0xffff0000, v51
	v_lshlrev_b32_e32 v93, 16, v52
	v_and_b32_e32 v52, 0xffff0000, v52
	v_lshlrev_b32_e32 v94, 16, v53
	v_and_b32_e32 v53, 0xffff0000, v53
	s_waitcnt lgkmcnt(1)
	v_mul_f32_e32 v32, v32, v91
	v_mul_f32_e32 v33, v33, v50
	v_mul_f32_e32 v34, v34, v92
	v_mul_f32_e32 v35, v35, v51
	s_waitcnt lgkmcnt(0)
	v_mul_f32_e32 v36, v36, v93
	v_mul_f32_e32 v37, v37, v52
	v_mul_f32_e32 v38, v38, v94
	v_mul_f32_e32 v39, v39, v53
	v_cvt_pk_bf16_f32 v32, v32, v33
	v_cvt_pk_bf16_f32 v33, v34, v35
	v_cvt_pk_bf16_f32 v34, v36, v37
	v_cvt_pk_bf16_f32 v35, v38, v39
	global_store_dwordx4 v[54:55], v[32:35], off
	s_waitcnt lgkmcnt(0)
	ds_write2_b32 v86, v49, v60 offset1:32
	ds_write2_b32 v86, v61, v62 offset0:64 offset1:96
	ds_write2_b32 v87, v63, v68 offset1:32
	ds_write2_b32 v87, v69, v90 offset0:64 offset1:96
	ds_write2_b32 v88, v40, v41 offset1:32
	ds_write2_b32 v88, v42, v43 offset0:64 offset1:96
	ds_write2_b32 v89, v44, v45 offset1:32
	ds_write2_b32 v89, v46, v47 offset0:64 offset1:96
	s_waitcnt lgkmcnt(0)
	ds_read_b128 v[36:39], v48 offset:16384
	ds_read_b128 v[40:43], v48 offset:16400
	v_lshl_add_u64 v[44:45], v[58:59], 0, s[2:3]
	v_lshl_add_u64 v[46:47], v[56:57], 0, s[2:3]
	s_waitcnt vmcnt(6)
	v_mov_b32_e32 v32, v226
	v_mov_b32_e32 v33, v227
	v_mov_b32_e32 v34, v228
	v_mov_b32_e32 v35, v229
	v_lshlrev_b32_e32 v49, 16, v32
	v_and_b32_e32 v32, 0xffff0000, v32
	v_lshlrev_b32_e32 v50, 16, v33
	v_and_b32_e32 v33, 0xffff0000, v33
	v_lshlrev_b32_e32 v51, 16, v34
	v_and_b32_e32 v34, 0xffff0000, v34
	v_lshlrev_b32_e32 v52, 16, v35
	v_and_b32_e32 v35, 0xffff0000, v35
	s_waitcnt lgkmcnt(1)
	v_mul_f32_e32 v32, v37, v32
	v_mul_f32_e32 v33, v39, v33
	s_waitcnt lgkmcnt(0)
	v_mul_f32_e32 v34, v41, v34
	v_mul_f32_e32 v35, v43, v35
	v_mul_f32_e32 v36, v36, v49
	v_mul_f32_e32 v37, v38, v50
	v_mul_f32_e32 v38, v40, v51
	v_mul_f32_e32 v39, v42, v52
	v_cvt_pk_bf16_f32 v32, v36, v32
	v_cvt_pk_bf16_f32 v33, v37, v33
	v_cvt_pk_bf16_f32 v34, v38, v34
	v_cvt_pk_bf16_f32 v35, v39, v35
	global_store_dwordx4 v[58:59], v[32:35], off offset:64
	v_mul_f32_e32 v40, v16, v72
	v_mul_f32_e32 v41, v17, v73
	v_mul_f32_e32 v42, v18, v74
	v_mul_f32_e32 v43, v19, v75
	v_mul_f32_e32 v46, v20, v76
	v_mul_f32_e32 v47, v21, v77
	v_mul_f32_e32 v49, v22, v78
	v_mul_f32_e32 v50, v23, v79
	ds_read_b128 v[16:19], v48 offset:18432
	ds_read_b128 v[20:23], v48 offset:18448
	v_mov_b64_e32 v[36:37], v[66:67]
	v_mov_b64_e32 v[38:39], v[64:65]
	s_waitcnt vmcnt(6)
	v_mov_b32_e32 v32, v230
	v_mov_b32_e32 v33, v231
	v_mov_b32_e32 v34, v232
	v_mov_b32_e32 v35, v233
	v_lshlrev_b32_e32 v51, 16, v32
	v_and_b32_e32 v32, 0xffff0000, v32
	v_lshlrev_b32_e32 v52, 16, v33
	v_and_b32_e32 v33, 0xffff0000, v33
	v_lshlrev_b32_e32 v53, 16, v34
	v_and_b32_e32 v34, 0xffff0000, v34
	v_lshlrev_b32_e32 v54, 16, v35
	v_and_b32_e32 v35, 0xffff0000, v35
	s_waitcnt lgkmcnt(1)
	v_mul_f32_e32 v16, v16, v51
	v_mul_f32_e32 v17, v17, v32
	v_mul_f32_e32 v18, v18, v52
	v_mul_f32_e32 v19, v19, v33
	s_waitcnt lgkmcnt(0)
	v_mul_f32_e32 v20, v20, v53
	v_mul_f32_e32 v21, v21, v34
	v_mul_f32_e32 v22, v22, v54
	v_mul_f32_e32 v23, v23, v35
	v_cvt_pk_bf16_f32 v16, v16, v17
	v_cvt_pk_bf16_f32 v17, v18, v19
	v_cvt_pk_bf16_f32 v18, v20, v21
	v_cvt_pk_bf16_f32 v19, v22, v23
	global_store_dwordx4 v[44:45], v[16:19], off offset:64
	s_waitcnt lgkmcnt(0)
	ds_write2_b32 v86, v40, v41 offset1:32
	ds_write2_b32 v86, v42, v43 offset0:64 offset1:96
	ds_write2_b32 v87, v46, v47 offset1:32
	ds_write2_b32 v87, v49, v50 offset0:64 offset1:96
	ds_write2_b32 v88, v24, v25 offset1:32
	ds_write2_b32 v88, v26, v27 offset0:64 offset1:96
	ds_write2_b32 v89, v28, v29 offset1:32
	ds_write2_b32 v89, v30, v31 offset0:64 offset1:96
	s_waitcnt lgkmcnt(0)
	ds_read_b128 v[20:23], v48 offset:16384
	ds_read_b128 v[24:27], v48 offset:16400
	v_lshl_add_u64 v[28:29], v[38:39], 0, s[2:3]
	v_lshl_add_u64 v[30:31], v[36:37], 0, s[2:3]
	s_waitcnt vmcnt(6)
	v_mov_b32_e32 v16, v234
	v_mov_b32_e32 v17, v235
	v_mov_b32_e32 v18, v236
	v_mov_b32_e32 v19, v237
	v_lshlrev_b32_e32 v32, 16, v16
	v_and_b32_e32 v16, 0xffff0000, v16
	v_lshlrev_b32_e32 v33, 16, v17
	v_and_b32_e32 v17, 0xffff0000, v17
	v_lshlrev_b32_e32 v34, 16, v18
	v_and_b32_e32 v18, 0xffff0000, v18
	v_lshlrev_b32_e32 v35, 16, v19
	v_and_b32_e32 v19, 0xffff0000, v19
	s_waitcnt lgkmcnt(1)
	v_mul_f32_e32 v16, v21, v16
	v_mul_f32_e32 v17, v23, v17
	s_waitcnt lgkmcnt(0)
; #define LAS __attribute__((address_space(3)))
; __device__ __forceinline__ unsigned cvt_pk_bf16(float lo, float hi) { unsigned r; asm volatile("v_cvt_pk_bf16_f32 %0, %1, %2" : "=v"(r) : "v"(lo), "v"(hi)); return r; }
; __device__ __forceinline__ float bf_lo(unsigned w) { return __uint_as_float(w << 16); }
; __device__ __forceinline__ float bf_hi(unsigned w) { return __uint_as_float(w & 0xffff0000u); }
; __device__ __forceinline__ int crow(int r, int hi) { return (r & 3) + 8 * (r >> 2) + 4 * hi; }
; #define WAITV_BAR(N) asm volatile("s_waitcnt vmcnt(" #N ") lgkmcnt(0)\n\ts_barrier" ::: "memory")
; __device__ __forceinline__ DmaOff dma_offsets(int wid, int lane) {
;     ...
;     for (int i = 0; i < 2; ++i) { const int pc = wid * 2 + i, q = pc * 64 + lane;
;         const int row = q >> 4, j = (q & 15) ^ (row & 7); d.k[i] = (unsigned)(row * 256 + j * 16);
;         const int s = q >> 5, w = q & 31, kk = (s >> 2) * 8 + (w >> 2), c = (s & 3) * 32 + (w & 3) * 8, k = (kk & ~0xC) | ((kk & 4) << 1) | ((kk & 8) >> 1);
;         d.v[i] = (unsigned)(k * 256 + c * 2); }
; __device__ __forceinline__ void fox_block(const BlockRef& cur, const BlockRef& nxt, char* lds, Seam& S, const int tid) {
;     ...
;     for (int d0 = 0; d0 < 4; ++d0) {
; #pragma unroll
;         for (int r = 0; r < 16; ++r) stg[crow(r, hi) * 32 + r32] = o[d0][r] * rli[r];
;         asm volatile("s_waitcnt lgkmcnt(0)" ::: "memory");
;         gbf16* op = obase; const gbf16* zp = zbase;
; #pragma unroll
;         for (int i = 0; i < 2; ++i) {
;             asm volatile("" : "+v"(op), "+v"(zp));
;             const f32x4 v0 = *(const LAS f32x4*)(stg + (er + 16 * i) * 32 + 8 * eq), v1 = *(const LAS f32x4*)(stg + (er + 16 * i) * 32 + 8 * eq + 4);
;             const u32x4 z = __builtin_nontemporal_load((const gu32x4*)(zp + d0 * 32));
;             u32x4 w; w.x = cvt_pk_bf16(v0.x * bf_lo(z.x), v0.y * bf_hi(z.x)); w.y = cvt_pk_bf16(v0.z * bf_lo(z.y), v0.w * bf_hi(z.y));
;             w.z = cvt_pk_bf16(v1.x * bf_lo(z.z), v1.y * bf_hi(z.z)); w.w = cvt_pk_bf16(v1.z * bf_lo(z.w), v1.w * bf_hi(z.w));
;             *(gu32x4*)(op + d0 * 32) = w;
;             op += 16 * LD; zp += 16 * LD; }
;         asm volatile("s_waitcnt lgkmcnt(0)" ::: "memory"); }
;     WAITV_BAR(0);
	v_mul_f32_e32 v18, v25, v18
	v_mul_f32_e32 v19, v27, v19
	v_mul_f32_e32 v20, v20, v32
	v_mul_f32_e32 v21, v22, v33
	v_mul_f32_e32 v22, v24, v34
	v_mul_f32_e32 v23, v26, v35
	v_cvt_pk_bf16_f32 v16, v20, v16
	v_cvt_pk_bf16_f32 v17, v21, v17
	v_cvt_pk_bf16_f32 v18, v22, v18
	v_cvt_pk_bf16_f32 v19, v23, v19
	global_store_dwordx4 v[38:39], v[16:19], off offset:128
	v_mul_f32_e32 v20, v0, v72
	v_mul_f32_e32 v21, v1, v73
	v_mul_f32_e32 v22, v2, v74
	v_mul_f32_e32 v23, v3, v75
	v_mul_f32_e32 v24, v4, v76
	v_mul_f32_e32 v25, v5, v77
	v_mul_f32_e32 v26, v6, v78
	v_mul_f32_e32 v27, v7, v79
	ds_read_b128 v[0:3], v48 offset:18432
	ds_read_b128 v[4:7], v48 offset:18448
	s_waitcnt vmcnt(6)
	v_mov_b32_e32 v16, v238
	v_mov_b32_e32 v17, v239
	v_mov_b32_e32 v18, v240
	v_mov_b32_e32 v19, v241
	v_lshlrev_b32_e32 v30, 16, v16
	v_and_b32_e32 v16, 0xffff0000, v16
	v_lshlrev_b32_e32 v31, 16, v17
	v_and_b32_e32 v17, 0xffff0000, v17
	v_lshlrev_b32_e32 v32, 16, v18
	v_and_b32_e32 v18, 0xffff0000, v18
	v_lshlrev_b32_e32 v33, 16, v19
	v_and_b32_e32 v19, 0xffff0000, v19
	s_waitcnt lgkmcnt(1)
	v_mul_f32_e32 v0, v0, v30
	v_mul_f32_e32 v1, v1, v16
	v_mul_f32_e32 v2, v2, v31
	v_mul_f32_e32 v3, v3, v17
	s_waitcnt lgkmcnt(0)
	v_mul_f32_e32 v4, v4, v32
	v_mul_f32_e32 v5, v5, v18
	v_mul_f32_e32 v6, v6, v33
	v_mul_f32_e32 v7, v7, v19
	v_cvt_pk_bf16_f32 v0, v0, v1
	v_cvt_pk_bf16_f32 v1, v2, v3
	v_cvt_pk_bf16_f32 v2, v4, v5
	v_cvt_pk_bf16_f32 v3, v6, v7
	global_store_dwordx4 v[28:29], v[0:3], off offset:128
	s_waitcnt lgkmcnt(0)
	ds_write2_b32 v86, v20, v21 offset1:32
	ds_write2_b32 v86, v22, v23 offset0:64 offset1:96
	ds_write2_b32 v87, v24, v25 offset1:32
	ds_write2_b32 v87, v26, v27 offset0:64 offset1:96
	ds_write2_b32 v88, v8, v9 offset1:32
	ds_write2_b32 v88, v10, v11 offset0:64 offset1:96
	ds_write2_b32 v89, v12, v13 offset1:32
	ds_write2_b32 v89, v14, v15 offset0:64 offset1:96
	s_waitcnt lgkmcnt(0)
	ds_read_b128 v[4:7], v48 offset:16384
	ds_read_b128 v[8:11], v48 offset:16400
	v_lshl_add_u64 v[12:13], v[64:65], 0, s[2:3]
	v_lshl_add_u64 v[14:15], v[66:67], 0, s[2:3]
	v_readfirstlane_b32 s3, v155
	s_ashr_i32 s70, s3, 6
	s_lshl_b32 s5, s70, 7
	s_and_b32 s3, s3, 0x3fffffc0
	v_readlane_b32 s2, v248, 61
	s_lshl_b32 s3, s3, 2
	s_and_b32 s2, s2, 0x700
	s_lshl_b32 s71, s70, 5
	s_add_i32 s3, s3, 0
	s_add_i32 s3, s3, 0x18000
	s_waitcnt vmcnt(6)
	v_mov_b32_e32 v0, v242
	v_mov_b32_e32 v1, v243
	v_mov_b32_e32 v2, v244
	v_mov_b32_e32 v3, v245
	v_lshlrev_b32_e32 v16, 16, v0
	v_and_b32_e32 v0, 0xffff0000, v0
	v_lshlrev_b32_e32 v17, 16, v1
	v_and_b32_e32 v1, 0xffff0000, v1
	v_lshlrev_b32_e32 v18, 16, v2
	v_and_b32_e32 v2, 0xffff0000, v2
	v_lshlrev_b32_e32 v19, 16, v3
	v_and_b32_e32 v3, 0xffff0000, v3
	s_waitcnt lgkmcnt(1)
	v_mul_f32_e32 v0, v5, v0
	v_mul_f32_e32 v1, v7, v1
	s_waitcnt lgkmcnt(0)
	v_mul_f32_e32 v2, v9, v2
	v_mul_f32_e32 v3, v11, v3
	v_mul_f32_e32 v4, v4, v16
	v_mul_f32_e32 v5, v6, v17
	v_mul_f32_e32 v6, v8, v18
	v_mul_f32_e32 v7, v10, v19
	v_cvt_pk_bf16_f32 v0, v4, v0
	v_cvt_pk_bf16_f32 v1, v5, v1
	v_cvt_pk_bf16_f32 v2, v6, v2
	v_cvt_pk_bf16_f32 v3, v7, v3
	global_store_dwordx4 v[64:65], v[0:3], off offset:192
	global_load_dwordx4 v[0:3], v[14:15], off offset:192 nt
	v_or_b32_e32 v4, s5, v198
	s_ashr_i32 s5, s5, 4
	v_bitop3_b32 v36, s5, -13, v191 bitop3:0xc8
	s_lshr_b32 s5, s5, 1
	v_ashrrev_i32_e32 v5, 4, v4
	s_and_b32 s5, s5, 4
	v_or_b32_e32 v14, 64, v4
	v_bitop3_b32 v4, v5, v203, 15 bitop3:0x6c
	v_lshlrev_b32_e32 v5, 8, v5
	v_or3_b32 v6, v36, s5, v200
	v_lshl_or_b32 v128, v4, 4, v5
	v_lshlrev_b32_e32 v17, 8, v6
	ds_read_b128 v[4:7], v48 offset:18432
	ds_read_b128 v[8:11], v48 offset:18448
	v_ashrrev_i32_e32 v15, 4, v14
	v_bitop3_b32 v16, v15, v203, 15 bitop3:0x6c
	v_or_b32_e32 v134, v17, v204
	s_waitcnt vmcnt(0)
	v_lshlrev_b32_e32 v18, 16, v0
	v_and_b32_e32 v0, 0xffff0000, v0
	v_lshlrev_b32_e32 v19, 16, v1
	v_and_b32_e32 v1, 0xffff0000, v1
	v_lshlrev_b32_e32 v20, 16, v2
	v_and_b32_e32 v2, 0xffff0000, v2
	v_lshlrev_b32_e32 v21, 16, v3
	v_and_b32_e32 v3, 0xffff0000, v3
	s_waitcnt lgkmcnt(1)
	v_mul_f32_e32 v0, v5, v0
	v_mul_f32_e32 v1, v7, v1
	s_waitcnt lgkmcnt(0)
	v_mul_f32_e32 v2, v9, v2
	v_mul_f32_e32 v3, v11, v3
	v_mul_f32_e32 v4, v4, v18
	v_mul_f32_e32 v5, v6, v19
	v_mul_f32_e32 v6, v8, v20
	v_mul_f32_e32 v7, v10, v21
	v_cvt_pk_bf16_f32 v0, v4, v0
	v_cvt_pk_bf16_f32 v1, v5, v1
	v_cvt_pk_bf16_f32 v2, v6, v2
	v_cvt_pk_bf16_f32 v3, v7, v3
	global_store_dwordx4 v[12:13], v[0:3], off offset:192
	s_waitcnt lgkmcnt(0)
	s_waitcnt vmcnt(0) lgkmcnt(0)
	s_barrier
; #define LAS __attribute__((address_space(3)))
; #define SBAR() __builtin_amdgcn_sched_barrier(0)
; __device__ __forceinline__ int v_rd_base(int lane) { return ((lane & 3) << 3) | (((lane >> 2) & 3) << 6) | (((lane >> 4) & 1) << 5) | (((lane >> 5) & 1) << 8); }
; #define WAITV_BAR(N) asm volatile("s_waitcnt vmcnt(" #N ") lgkmcnt(0)\n\ts_barrier" ::: "memory")
; #define DMA_K(t, slot) do { _Pragma("unroll") for (int i_ = 0; i_ < 2; ++i_) __builtin_amdgcn_global_load_lds((const unsigned*)((const char*)Kh + (size_t)(t) * (KVBLK * D * 2) + dof.k[i_]), \
;         (LAS unsigned*)((LAS unsigned char*)lds3 + OFF_K + (slot) + (wid * 2 + i_) * 1024), 16, 0, 0); } while (0)
; __device__ __forceinline__ void qkt(f32x16& p0, f32x16& p1, const char* Kslot, int r32, int hi, const bf16x8* qr, const LAS f32x4* cp) {
; #pragma unroll
;     for (int g = 0; g < 4; ++g) { const f32x4 c0 = cp[2 * g], c1 = cp[8 + 2 * g];
; #pragma unroll
;         for (int j = 0; j < 4; ++j) { p0[4 * g + j] = c0[j]; p1[4 * g + j] = c1[j]; } }
;     const char* kb[4];
; #pragma unroll
;     for (int dd = 0; dd < 4; ++dd) kb[dd] = Kslot + KSWZ(r32, (dd * 16 + hi * 8) * 2);
; #pragma unroll
;     for (int d0 = 0; d0 < 8; ++d0) { const char* a = kb[d0 & 3] + (d0 >> 2) * 128;
;         bf16x8 b0 = *reinterpret_cast<const bf16x8*>(a);
;         bf16x8 b1 = *reinterpret_cast<const bf16x8*>(a + 32 * 256);
;         p0 = __builtin_amdgcn_mfma_f32_32x32x16_bf16(b0, qr[d0], p0, 0, 0, 0);
;         p1 = __builtin_amdgcn_mfma_f32_32x32x16_bf16(b1, qr[d0], p1, 0, 0, 0); }
; __device__ __forceinline__ void fox_block(const BlockRef& cur, const BlockRef& nxt, char* lds, Seam& S, const int tid) {
;     ...
;     float m_reg = -1e30f, l_reg = 0; f32x16 o[4] = {};
;     const DmaOff dof = dma_offsets(wid, lane);
;     const int vb0 = (int)(uintptr_t)V_lds + v_rd_base(lane);
;     const bf16_t* Kh = cur.K; const bf16_t* Vh = cur.V;
;     ...
;     f32x16 pA0, pA1, pB0, pB1; float mnA, mnB, alA, alB; bf16x8 pa0, pa1, pa2, pa3;
;     int s_prev = 0, s_cur = 0, s_next = SLOT, s_nn = 2 * SLOT;
;     SBAR(); DMA_K(2, s_nn); DMA_V(1, s_next); SBAR();
;     qkt(pA0, pA1, K_lds + s_cur, r32, hi, S.qr, CTP(0));
;     mask_meta(pA0, pA1); partialSM(pA0, pA1, m_reg, mnA, alA);
;     SBAR(); WAITV_BAR(4);
;     ROT();
	s_nop 1
	v_lshlrev_b32_e32 v0, 8, v15
	v_lshl_or_b32 v138, v16, 4, v0
	v_and_or_b32 v0, v14, s6, v202
	v_lshl_or_b32 v136, v0, 1, v17
	s_lshl_b32 s6, s70, 11
	s_add_i32 s86, s6, 0
	s_add_i32 m0, s86, 0x14000
	v_readlane_b32 s6, v247, 24
	global_load_lds_dwordx4 v128, s[66:67]
	s_add_i32 m0, s86, 0x14400
	v_readlane_b32 s7, v247, 25
	global_load_lds_dwordx4 v138, s[66:67]
	s_add_i32 m0, s86, 0x4000
	v_mov_b32_e32 v139, v129
	s_add_i32 s88, s71, s4
	s_nop 0
	global_load_lds_dwordx4 v134, s[6:7]
	s_add_i32 m0, s86, 0x4400
	s_movk_i32 s73, 0x4000
	global_load_lds_dwordx4 v136, s[6:7]
	v_mov_b32_e32 v135, v129
	v_mov_b32_e32 v137, v129
	s_add_i32 s89, s89, 4
	ds_read_b128 v[16:19], v209 offset:57344
	ds_read_b128 v[0:3], v205 offset:128
	ds_read_b128 v[4:7], v205 offset:160
	ds_read_b128 v[8:11], v205 offset:192
	ds_read_b128 v[12:15], v205 offset:224
	v_xor_b32_e32 v249, 0x80, v209
	v_xor_b32_e32 v250, 0x80, v208
	v_xor_b32_e32 v251, 0x80, v207
	v_xor_b32_e32 v252, 0x80, v206
	ds_read_b128 v[20:23], v249 offset:57344
	s_mov_b32 s4, 0xff800000
	s_waitcnt lgkmcnt(0)
	v_mfma_f32_32x32x16_bf16 v[0:15], v[16:19], v[96:99], v[0:15]
	ds_read_b128 v[16:19], v208 offset:57344
	ds_read_b128 v[24:27], v250 offset:57344
	s_waitcnt lgkmcnt(0)
	v_mfma_f32_32x32x16_bf16 v[0:15], v[16:19], v[100:103], v[0:15]
	ds_read_b128 v[16:19], v207 offset:57344
	ds_read_b128 v[28:31], v251 offset:57344
	s_waitcnt lgkmcnt(0)
	v_mfma_f32_32x32x16_bf16 v[0:15], v[16:19], v[104:107], v[0:15]
	ds_read_b128 v[16:19], v206 offset:57344
	ds_read_b128 v[32:35], v252 offset:57344
	s_waitcnt lgkmcnt(0)
	v_mfma_f32_32x32x16_bf16 v[0:15], v[16:19], v[108:111], v[0:15]
	v_mfma_f32_32x32x16_bf16 v[0:15], v[20:23], v[112:115], v[0:15]
	v_mfma_f32_32x32x16_bf16 v[0:15], v[24:27], v[116:119], v[0:15]
	v_mfma_f32_32x32x16_bf16 v[0:15], v[28:31], v[120:123], v[0:15]
	v_mfma_f32_32x32x16_bf16 v[0:15], v[32:35], v[124:127], v[0:15]
	s_nop 11
	v_max3_f32 v0, v8, s4, v9
	v_max3_f32 v0, v0, v10, v11
	v_max3_f32 v0, v0, v12, v13
	v_max3_f32 v0, v0, v14, v15
	v_mov_b32_e32 v1, v0
	s_nop 1
	v_permlane32_swap_b32_e32 v0, v1
	v_max_f32_e32 v1, v1, v1
	v_max_f32_e32 v0, v0, v0
	v_max_f32_e32 v0, v0, v1
	v_add_f32_e32 v1, 0x7149f2ca, v0
	v_cmp_ge_f32_e32 vcc, s33, v1
	s_cmp_eq_u64 vcc, exec
	v_max_f32_e32 v2, 0xf149f2ca, v0
	s_cselect_b64 vcc, -1, 0
	v_cndmask_b32_e32 v144, v2, v189, vcc
	v_mov_b32_e32 v0, v9
	v_mov_b32_e32 v1, v10
	v_pk_add_f32 v[66:67], v[0:1], v[144:145] op_sel_hi:[1,0] neg_lo:[0,1] neg_hi:[0,1]
	v_mov_b32_e32 v0, v11
	v_mov_b32_e32 v1, v12
	v_pk_add_f32 v[68:69], v[0:1], v[144:145] op_sel_hi:[1,0] neg_lo:[0,1] neg_hi:[0,1]
	v_sub_f32_e32 v1, 0xf149f2ca, v2
	v_mov_b32_e32 v131, v8
	v_mov_b32_e32 v0, v13
	v_exp_f32_e32 v2, v1
	v_mov_b32_e32 v1, v14
	s_add_i32 s2, s2, s71
	v_pk_add_f32 v[64:65], v[130:131], v[144:145] op_sel_hi:[1,0] neg_lo:[0,1] neg_hi:[0,1]
	v_pk_add_f32 v[70:71], v[0:1], v[144:145] op_sel_hi:[1,0] neg_lo:[0,1] neg_hi:[0,1]
	v_or_b32_e32 v0, s2, v199
	v_exp_f32_e32 v178, v64
	v_sub_u32_e32 v173, v0, v201
	v_add_u32_e32 v0, v36, v200
	v_add_lshl_u32 v0, v0, s5, 8
	s_waitcnt vmcnt(4) lgkmcnt(0)
	s_barrier
	v_or_b32_e32 v1, v0, v211
	v_mov_b32_e32 v48, v129
	v_mov_b32_e32 v49, v129
	v_sub_f32_e32 v155, v15, v144
	v_cndmask_b32_e64 v174, v2, 1.0, vcc
	v_add_u32_e32 v140, v1, v210
	v_or3_b32 v142, v0, v212, v210
	v_mov_b32_e32 v50, v129
	v_mov_b32_e32 v51, v129
	v_mov_b32_e32 v52, v129
	v_mov_b32_e32 v53, v129
	v_mov_b32_e32 v54, v129
	v_mov_b32_e32 v55, v129
	v_mov_b32_e32 v56, v129
	v_mov_b32_e32 v57, v129
	v_mov_b32_e32 v58, v129
	v_mov_b32_e32 v59, v129
	v_mov_b32_e32 v60, v129
	v_mov_b32_e32 v61, v129
	v_mov_b32_e32 v62, v129
	v_mov_b32_e32 v63, v129
	v_mov_b64_e32 v[32:33], v[48:49]
	v_mov_b64_e32 v[16:17], v[48:49]
	v_mov_b64_e32 v[0:1], v[48:49]
	v_add_u32_e32 v171, s3, v133
	v_lshl_add_u32 v131, v201, 2, s3
	v_mov_b32_e32 v141, v129
	v_mov_b32_e32 v143, v129
	s_mov_b32 s2, 0
	v_mov_b32_e32 v172, 0
	s_mov_b32 s90, 0x8000
	s_movk_i32 s91, 0xbf
	v_mov_b64_e32 v[34:35], v[50:51]
	v_mov_b64_e32 v[36:37], v[52:53]
	v_mov_b64_e32 v[38:39], v[54:55]
	v_mov_b64_e32 v[40:41], v[56:57]
	v_mov_b64_e32 v[42:43], v[58:59]
	v_mov_b64_e32 v[44:45], v[60:61]
	v_mov_b64_e32 v[46:47], v[62:63]
	v_mov_b64_e32 v[18:19], v[50:51]
	v_mov_b64_e32 v[20:21], v[52:53]
	v_mov_b64_e32 v[22:23], v[54:55]
	v_mov_b64_e32 v[24:25], v[56:57]
	v_mov_b64_e32 v[26:27], v[58:59]
	v_mov_b64_e32 v[28:29], v[60:61]
	v_mov_b64_e32 v[30:31], v[62:63]
	v_mov_b64_e32 v[2:3], v[50:51]
	v_mov_b64_e32 v[4:5], v[52:53]
	v_mov_b64_e32 v[6:7], v[54:55]
	v_mov_b64_e32 v[8:9], v[56:57]
	v_mov_b64_e32 v[10:11], v[58:59]
	v_mov_b64_e32 v[12:13], v[60:61]
	v_mov_b64_e32 v[14:15], v[62:63]
	s_mov_b32 s72, 0
	v_mov_b32_e32 v211, v178
	v_mov_b32_e32 v208, v178
	v_mov_b32_e32 v210, v178
	v_mov_b32_e32 v206, v178
	v_mov_b32_e32 v209, v178
	v_mov_b32_e32 v205, v178
	v_mov_b32_e32 v207, v178
	v_mov_b32_e32 v202, v178
	v_mov_b32_e32 v204, v178
	v_mov_b32_e32 v200, v178
	v_mov_b32_e32 v203, v178
	v_mov_b32_e32 v198, v178
	v_mov_b32_e32 v201, v178
	v_mov_b32_e32 v179, v178
	v_mov_b32_e32 v199, v178
	v_mov_b32_e32 v158, v64
	v_mov_b32_e32 v159, v64
	v_mov_b32_e32 v162, v64
	v_mov_b32_e32 v163, v64
	v_mov_b32_e32 v166, v64
	v_mov_b32_e32 v167, v64
	v_mov_b32_e32 v156, v64
	v_mov_b32_e32 v157, v64
	v_mov_b32_e32 v160, v65
	v_mov_b32_e32 v161, v66
	v_mov_b32_e32 v164, v67
	v_mov_b32_e32 v165, v68
	v_mov_b32_e32 v168, v69
	v_mov_b32_e32 v169, v70
	v_mov_b32_e32 v154, v71
	v_readlane_b32 s96, v247, 9
	v_readlane_b32 s97, v247, 8

; #define LAS __attribute__((address_space(3)))
; __device__ __forceinline__ void finishSM(f32x16& p0, f32x16& p1, float alpha, float& l_reg, bf16x8& pa0, bf16x8& pa1, bf16x8& pa2, bf16x8& pa3) {
; #pragma unroll
;     for (int r = 0; r < 16; ++r) p1[r] = __builtin_amdgcn_exp2f(p1[r]);
;     float ps = 0;
; #pragma unroll
;     for (int r = 0; r < 16; ++r) ps += p0[r];
; #pragma unroll
;     for (int r = 0; r < 16; ++r) ps += p1[r];
;     { auto rr = __builtin_amdgcn_permlane32_swap(__float_as_uint(ps), __float_as_uint(ps), false, false);
;       ps = __uint_as_float(rr[0]) + __uint_as_float(rr[1]); }
;     l_reg = l_reg * alpha + ps;
;     ...
;     PK4(p0, 0, pa0); PK4(p0, 8, pa1); PK4(p1, 0, pa2); PK4(p1, 8, pa3);
; __device__ __forceinline__ void qkt(f32x16& p0, f32x16& p1, const char* Kslot, int r32, int hi, const bf16x8* qr, const LAS f32x4* cp) {
; #pragma unroll
;     for (int g = 0; g < 4; ++g) { const f32x4 c0 = cp[2 * g], c1 = cp[8 + 2 * g];
; #pragma unroll
;         for (int j = 0; j < 4; ++j) { p0[4 * g + j] = c0[j]; p1[4 * g + j] = c1[j]; } }
;     const char* kb[4];
; #pragma unroll
;     for (int dd = 0; dd < 4; ++dd) kb[dd] = Kslot + KSWZ(r32, (dd * 16 + hi * 8) * 2);
; #pragma unroll
;     for (int d0 = 0; d0 < 8; ++d0) { const char* a = kb[d0 & 3] + (d0 >> 2) * 128;
;         bf16x8 b0 = *reinterpret_cast<const bf16x8*>(a);
;         bf16x8 b1 = *reinterpret_cast<const bf16x8*>(a + 32 * 256);
;         p0 = __builtin_amdgcn_mfma_f32_32x32x16_bf16(b0, qr[d0], p0, 0, 0, 0);
;         p1 = __builtin_amdgcn_mfma_f32_32x32x16_bf16(b1, qr[d0], p1, 0, 0, 0); }
.LBB0_558:
	s_add_i32 s3, s86, s90
	v_lshl_add_u64 v[150:151], s[82:83], 0, v[140:141]
	v_lshl_add_u64 v[64:65], v[150:151], 0, s[84:85]
	s_mov_b32 m0, s3
	v_lshl_add_u64 v[152:153], s[82:83], 0, v[142:143]
	global_load_lds_dwordx4 v[64:65], off
	v_lshl_add_u64 v[64:65], v[152:153], 0, s[84:85]
	s_add_i32 m0, s3, 0x400
	s_nop 0
	global_load_lds_dwordx4 v[64:65], off
	s_add_i32 s3, s73, 0
	v_add_u32_e32 v175, s3, v193
	ds_read_b128 v[80:83], v197
	ds_read_b128 v[84:87], v197 offset:32
	ds_read_b128 v[64:67], v197 offset:128
	ds_read_b128 v[68:71], v197 offset:160
	ds_read_b128 v[88:91], v197 offset:64
	ds_read_b128 v[72:75], v197 offset:192
	ds_read_b128 v[92:95], v197 offset:96
	ds_read_b128 v[76:79], v197 offset:224
	ds_read_b128 v[212:215], v175 offset:49152
	ds_read_b128 v[216:219], v175 offset:57344
	v_add_u32_e32 v176, s3, v194
	v_add_u32_e32 v177, s3, v195
	s_waitcnt lgkmcnt(0)
	v_mfma_f32_32x32x16_bf16 v[80:95], v[212:215], v[96:99], v[80:95]
	v_add_u32_e32 v220, s3, v196
	v_exp_f32_e32 v163, v163
	v_exp_f32_e32 v166, v166
	v_exp_f32_e32 v167, v167
	v_exp_f32_e32 v168, v168
	v_exp_f32_e32 v169, v169
	v_exp_f32_e32 v221, v155
	v_mfma_f32_32x32x16_bf16 v[64:79], v[216:219], v[96:99], v[64:79]
	ds_read_b128 v[212:215], v176 offset:49152
	ds_read_b128 v[216:219], v176 offset:57344
	s_waitcnt lgkmcnt(0)
	v_mfma_f32_32x32x16_bf16 v[80:95], v[212:215], v[100:103], v[80:95]
	v_mfma_f32_32x32x16_bf16 v[64:79], v[216:219], v[100:103], v[64:79]
	ds_read_b128 v[212:215], v177 offset:49152
	ds_read_b128 v[216:219], v177 offset:57344
	s_waitcnt lgkmcnt(0)
	v_mfma_f32_32x32x16_bf16 v[80:95], v[212:215], v[104:107], v[80:95]
	v_mfma_f32_32x32x16_bf16 v[64:79], v[216:219], v[104:107], v[64:79]
	ds_read_b128 v[212:215], v220 offset:49152
	ds_read_b128 v[216:219], v220 offset:57344
	s_waitcnt lgkmcnt(0)
	v_mfma_f32_32x32x16_bf16 v[80:95], v[212:215], v[108:111], v[80:95]
	v_mfma_f32_32x32x16_bf16 v[64:79], v[216:219], v[108:111], v[64:79]
	v_xor_b32_e32 v249, 0x80, v175
	v_xor_b32_e32 v250, 0x80, v176
	v_xor_b32_e32 v251, 0x80, v177
	v_xor_b32_e32 v252, 0x80, v220
	ds_read_b128 v[212:215], v249 offset:49152
	ds_read_b128 v[216:219], v249 offset:57344
	s_waitcnt lgkmcnt(0)
	v_mfma_f32_32x32x16_bf16 v[80:95], v[212:215], v[112:115], v[80:95]
	v_mfma_f32_32x32x16_bf16 v[64:79], v[216:219], v[112:115], v[64:79]
	ds_read_b128 v[212:215], v250 offset:49152
	ds_read_b128 v[216:219], v250 offset:57344
	s_waitcnt lgkmcnt(0)
	v_mfma_f32_32x32x16_bf16 v[80:95], v[212:215], v[116:119], v[80:95]
	v_mfma_f32_32x32x16_bf16 v[64:79], v[216:219], v[116:119], v[64:79]
	ds_read_b128 v[212:215], v251 offset:49152
	ds_read_b128 v[216:219], v251 offset:57344
	v_exp_f32_e32 v177, v158
	s_waitcnt lgkmcnt(0)
	v_mfma_f32_32x32x16_bf16 v[80:95], v[212:215], v[120:123], v[80:95]
	v_mfma_f32_32x32x16_bf16 v[64:79], v[216:219], v[120:123], v[64:79]
	ds_read_b128 v[212:215], v252 offset:49152
	ds_read_b128 v[216:219], v252 offset:57344
	v_exp_f32_e32 v220, v154
	v_add_f32_e32 v154, 0, v178
	v_add_f32_e32 v154, v211, v154
	v_add_f32_e32 v154, v208, v154
	v_add_f32_e32 v154, v210, v154
	v_add_f32_e32 v154, v206, v154
	v_add_f32_e32 v154, v209, v154
	v_add_f32_e32 v154, v205, v154
	v_add_f32_e32 v154, v207, v154
	v_add_f32_e32 v154, v202, v154
	v_add_f32_e32 v154, v204, v154
	v_add_f32_e32 v154, v200, v154
	v_add_f32_e32 v154, v203, v154
	v_add_f32_e32 v154, v198, v154
	s_waitcnt lgkmcnt(0)
	v_mfma_f32_32x32x16_bf16 v[80:95], v[212:215], v[124:127], v[80:95]
	v_exp_f32_e32 v212, v159
	v_add_f32_e32 v154, v201, v154
	v_exp_f32_e32 v213, v162
	v_add_f32_e32 v154, v179, v154
	v_add_f32_e32 v154, v199, v154
	v_add_f32_e32 v154, v177, v154
	v_add_f32_e32 v154, v212, v154
	v_exp_f32_e32 v214, v156
	v_add_f32_e32 v154, v213, v154
	v_exp_f32_e32 v215, v157
	v_add_f32_e32 v154, v163, v154
	v_mfma_f32_32x32x16_bf16 v[64:79], v[216:219], v[124:127], v[64:79]
	v_exp_f32_e32 v216, v160
	v_add_f32_e32 v154, v166, v154
	v_exp_f32_e32 v217, v161
	v_add_f32_e32 v154, v167, v154
	v_exp_f32_e32 v218, v164
	v_add_f32_e32 v154, v214, v154
	v_exp_f32_e32 v219, v165
	v_add_f32_e32 v154, v215, v154
	v_add_f32_e32 v154, v216, v154
	v_add_f32_e32 v154, v217, v154
	v_add_f32_e32 v154, v218, v154
	v_add_f32_e32 v154, v219, v154
	v_add_f32_e32 v154, v168, v154
	v_add_f32_e32 v154, v169, v154
	v_add_f32_e32 v154, v220, v154
	v_add_f32_e32 v175, v221, v154
	v_mov_b32_e32 v176, v175
	s_nop 1
	v_permlane32_swap_b32_e32 v175, v176
	v_cvt_pk_bf16_f32 v154, v178, v211
	v_cvt_pk_bf16_f32 v155, v208, v210
	v_cvt_pk_bf16_f32 v156, v206, v209
	v_cvt_pk_bf16_f32 v157, v205, v207
	v_cvt_pk_bf16_f32 v158, v202, v204
	v_cvt_pk_bf16_f32 v159, v200, v203
	v_cvt_pk_bf16_f32 v160, v198, v201
	v_cvt_pk_bf16_f32 v161, v179, v199
	v_cvt_pk_bf16_f32 v162, v177, v212
	v_cvt_pk_bf16_f32 v163, v213, v163
	v_cvt_pk_bf16_f32 v164, v166, v167
	v_cvt_pk_bf16_f32 v165, v214, v215
	v_cvt_pk_bf16_f32 v166, v216, v217
	v_cvt_pk_bf16_f32 v167, v218, v219
	v_cvt_pk_bf16_f32 v168, v168, v169
	v_cvt_pk_bf16_f32 v169, v220, v221
	s_nop 0
	v_permlane32_swap_b32_e32 v154, v156
	v_permlane32_swap_b32_e32 v155, v157
	v_permlane32_swap_b32_e32 v158, v160
	v_permlane32_swap_b32_e32 v159, v161
	v_permlane32_swap_b32_e32 v162, v164
	v_permlane32_swap_b32_e32 v163, v165
	v_permlane32_swap_b32_e32 v166, v168
	v_permlane32_swap_b32_e32 v167, v169
	v_add_u32_e32 v177, s2, v192
	ds_read_b64_tr_b16 v[198:199], v177 offset:0
	ds_read_b64_tr_b16 v[200:201], v177 offset:0x800
	ds_read_b64_tr_b16 v[202:203], v177 offset:0x1000
	ds_read_b64_tr_b16 v[204:205], v177 offset:0x1800
	ds_read_b64_tr_b16 v[206:207], v177 offset:0x2000
	ds_read_b64_tr_b16 v[208:209], v177 offset:0x2800
	ds_read_b64_tr_b16 v[210:211], v177 offset:0x3000
	ds_read_b64_tr_b16 v[212:213], v177 offset:0x3800
	s_waitcnt lgkmcnt(4)
; #define SBAR() __builtin_amdgcn_sched_barrier(0)
; #define PV_RD(d0, kh, X) do { constexpr int b_ = v_rd_off(d0, 2 * (kh), 0); TRRD(X##l0, b_); TRRD(X##h0, b_ + 2048); TRRD(X##l1, b_ + 4096); TRRD(X##h1, b_ + 6144); } while (0)
; #define PV_MM(d0, X, PA, PB) do { \
;         o[d0] = __builtin_amdgcn_mfma_f32_32x32x16_bf16(PA, (bf16x8){X##l0[0], X##l0[1], X##l0[2], X##l0[3], X##h0[0], X##h0[1], X##h0[2], X##h0[3]}, o[d0], 0, 0, 0);   \
;         o[d0] = __builtin_amdgcn_mfma_f32_32x32x16_bf16(PB, (bf16x8){X##l1[0], X##l1[1], X##l1[2], X##l1[3], X##h1[0], X##h1[1], X##h1[2], X##h1[3]}, o[d0], 0, 0, 0); } while (0)
; #define PV_W4() do { asm volatile("s_waitcnt lgkmcnt(4)" ::: "memory"); SBAR(); } while (0)
; #define PV_W0() do { asm volatile("s_waitcnt lgkmcnt(0)" ::: "memory"); SBAR(); } while (0)
; __device__ __forceinline__ void mask_tile(f32x16& p0, f32x16& p1, int dq) {
;     const float NEG = -__builtin_inff();
; #pragma unroll
;     for (int r = 0; r < 16; ++r) { const int c = (r & 3) + 8 * (r >> 2); if (dq - c < 0) p0[r] = NEG; if (dq - c - 32 < 0) p1[r] = NEG; }
; }
; __device__ __forceinline__ void pv_tile(f32x16* o, int vb0, bf16x8 pa0, bf16x8 pa1, bf16x8 pa2, bf16x8 pa3) {
;     ...
;     s16x4 al0, al1, ah0, ah1, bl0, bl1, bh0, bh1;
;     PV_RD(0, 0, a);
;     PV_RD(0, 1, b); PV_W4(); PV_MM(0, a, pa0, pa1); SBAR();
;     PV_RD(1, 0, a); PV_W4(); PV_MM(0, b, pa2, pa3); SBAR();
;     PV_RD(1, 1, b); PV_W4(); PV_MM(1, a, pa0, pa1); SBAR();
;     PV_RD(2, 0, a); PV_W4(); PV_MM(1, b, pa2, pa3); SBAR();
;     PV_RD(2, 1, b); PV_W4(); PV_MM(2, a, pa0, pa1); SBAR();
;     PV_RD(3, 0, a); PV_W4(); PV_MM(2, b, pa2, pa3); SBAR();
;     PV_RD(3, 1, b); PV_W4(); PV_MM(3, a, pa0, pa1); SBAR();
;     PV_W0(); PV_MM(3, b, pa2, pa3);
	s_nop 0
	v_mfma_f32_32x32x16_bf16 v[48:63], v[154:157], v[198:201], v[48:63]
	v_mfma_f32_32x32x16_bf16 v[48:63], v[158:161], v[202:205], v[48:63]
	ds_read_b64_tr_b16 v[198:199], v177 offset:0x200
	ds_read_b64_tr_b16 v[200:201], v177 offset:0xa00
	ds_read_b64_tr_b16 v[202:203], v177 offset:0x1200
	ds_read_b64_tr_b16 v[204:205], v177 offset:0x1a00
	s_waitcnt lgkmcnt(4)
	v_mfma_f32_32x32x16_bf16 v[48:63], v[162:165], v[206:209], v[48:63]
	v_mfma_f32_32x32x16_bf16 v[48:63], v[166:169], v[210:213], v[48:63]
	ds_read_b64_tr_b16 v[206:207], v177 offset:0x2200
	ds_read_b64_tr_b16 v[208:209], v177 offset:0x2a00
	ds_read_b64_tr_b16 v[210:211], v177 offset:0x3200
	ds_read_b64_tr_b16 v[212:213], v177 offset:0x3a00
	s_waitcnt lgkmcnt(4)
	v_mfma_f32_32x32x16_bf16 v[32:47], v[154:157], v[198:201], v[32:47]
	v_mfma_f32_32x32x16_bf16 v[32:47], v[158:161], v[202:205], v[32:47]
	ds_read_b64_tr_b16 v[198:199], v177 offset:0x400
	ds_read_b64_tr_b16 v[200:201], v177 offset:0xc00
	ds_read_b64_tr_b16 v[202:203], v177 offset:0x1400
	ds_read_b64_tr_b16 v[204:205], v177 offset:0x1c00
	s_waitcnt lgkmcnt(4)
	v_mfma_f32_32x32x16_bf16 v[32:47], v[162:165], v[206:209], v[32:47]
	v_mfma_f32_32x32x16_bf16 v[32:47], v[166:169], v[210:213], v[32:47]
	ds_read_b64_tr_b16 v[206:207], v177 offset:0x2400
	ds_read_b64_tr_b16 v[208:209], v177 offset:0x2c00
	ds_read_b64_tr_b16 v[210:211], v177 offset:0x3400
	ds_read_b64_tr_b16 v[212:213], v177 offset:0x3c00
	s_waitcnt lgkmcnt(4)
	v_mfma_f32_32x32x16_bf16 v[16:31], v[154:157], v[198:201], v[16:31]
	v_mfma_f32_32x32x16_bf16 v[16:31], v[158:161], v[202:205], v[16:31]
	ds_read_b64_tr_b16 v[198:199], v177 offset:0x600
	ds_read_b64_tr_b16 v[200:201], v177 offset:0xe00
	ds_read_b64_tr_b16 v[202:203], v177 offset:0x1600
	ds_read_b64_tr_b16 v[204:205], v177 offset:0x1e00
	s_waitcnt lgkmcnt(4)
	v_mfma_f32_32x32x16_bf16 v[16:31], v[162:165], v[206:209], v[16:31]
	v_mfma_f32_32x32x16_bf16 v[16:31], v[166:169], v[210:213], v[16:31]
	ds_read_b64_tr_b16 v[206:207], v177 offset:0x2600
	ds_read_b64_tr_b16 v[208:209], v177 offset:0x2e00
	ds_read_b64_tr_b16 v[210:211], v177 offset:0x3600
	ds_read_b64_tr_b16 v[212:213], v177 offset:0x3e00
	s_waitcnt lgkmcnt(4)
	v_mfma_f32_32x32x16_bf16 v[0:15], v[154:157], v[198:201], v[0:15]
	v_mfma_f32_32x32x16_bf16 v[0:15], v[158:161], v[202:205], v[0:15]
	s_waitcnt lgkmcnt(0)
	v_mfma_f32_32x32x16_bf16 v[0:15], v[162:165], v[206:209], v[0:15]
	s_sub_i32 s2, s91, 64
	s_cmp_le_i32 s2, s88
	v_mfma_f32_32x32x16_bf16 v[0:15], v[166:169], v[210:213], v[0:15]
	s_cbranch_scc1 .LBB0_560
	v_cmp_gt_i32_e64 s[62:63], 26, v173
	v_cmp_gt_i32_e64 s[64:65], 27, v173
	v_cmp_gt_i32_e64 s[60:61], 25, v173
	s_and_b64 s[62:63], s[64:65], s[62:63]
	v_cmp_gt_i32_e64 s[58:59], 24, v173
	s_and_b64 s[60:61], s[62:63], s[60:61]
	v_cmp_gt_i32_e64 s[56:57], 19, v173
	s_and_b64 s[58:59], s[60:61], s[58:59]
	v_cmp_gt_i32_e64 s[54:55], 18, v173
	s_and_b64 s[56:57], s[58:59], s[56:57]
	v_cmp_gt_i32_e64 s[52:53], 17, v173
	s_and_b64 s[54:55], s[56:57], s[54:55]
	v_cmp_gt_i32_e64 s[50:51], 16, v173
	s_and_b64 s[52:53], s[54:55], s[52:53]
	v_cmp_gt_i32_e64 s[48:49], 11, v173
	s_and_b64 s[50:51], s[52:53], s[50:51]
	v_cmp_gt_i32_e64 s[46:47], 10, v173
	s_and_b64 s[48:49], s[50:51], s[48:49]
	v_cmp_gt_i32_e64 s[44:45], 9, v173
	s_and_b64 s[46:47], s[48:49], s[46:47]
	v_cmp_gt_i32_e64 s[42:43], 8, v173
	s_and_b64 s[44:45], s[46:47], s[44:45]
	v_cmp_gt_i32_e64 s[40:41], 3, v173
	s_and_b64 s[42:43], s[44:45], s[42:43]
	v_cmp_gt_i32_e64 s[38:39], 2, v173
	s_and_b64 s[40:41], s[42:43], s[40:41]
	v_cmp_gt_i32_e64 s[36:37], 1, v173
	s_and_b64 s[38:39], s[40:41], s[38:39]
	v_cmp_gt_i32_e64 s[34:35], 0, v173
	s_and_b64 s[36:37], s[38:39], s[36:37]
	s_and_b64 s[34:35], s[36:37], s[34:35]
	v_cmp_gt_i32_e64 s[28:29], 58, v173
	v_cndmask_b32_e64 v80, v80, v130, s[34:35]
	v_cmp_gt_i32_e64 s[34:35], 59, v173
	v_cmp_gt_i32_e64 s[26:27], 57, v173
	s_and_b64 s[28:29], s[34:35], s[28:29]
	v_cmp_gt_i32_e64 s[24:25], 56, v173
	s_and_b64 s[26:27], s[28:29], s[26:27]
	v_cmp_gt_i32_e64 s[22:23], 51, v173
	s_and_b64 s[24:25], s[26:27], s[24:25]
	v_cmp_gt_i32_e64 s[20:21], 50, v173
	s_and_b64 s[22:23], s[24:25], s[22:23]
	v_cmp_gt_i32_e64 s[18:19], 49, v173
	s_and_b64 s[20:21], s[22:23], s[20:21]
	v_cmp_gt_i32_e64 s[16:17], 48, v173
	s_and_b64 s[18:19], s[20:21], s[18:19]
	v_cmp_gt_i32_e64 s[14:15], 43, v173
	s_and_b64 s[16:17], s[18:19], s[16:17]
	v_cmp_gt_i32_e64 s[12:13], 42, v173
	s_and_b64 s[14:15], s[16:17], s[14:15]
	v_cmp_gt_i32_e64 s[10:11], 41, v173
	s_and_b64 s[12:13], s[14:15], s[12:13]
	v_cmp_gt_i32_e64 s[8:9], 40, v173
	s_and_b64 s[10:11], s[12:13], s[10:11]
	v_cmp_gt_i32_e64 s[6:7], 35, v173
	s_and_b64 s[8:9], s[10:11], s[8:9]
	v_cmp_gt_i32_e64 s[4:5], 34, v173
	s_and_b64 s[6:7], s[8:9], s[6:7]
	v_cmp_gt_i32_e64 s[2:3], 33, v173
	s_and_b64 s[4:5], s[6:7], s[4:5]
	v_cmp_gt_i32_e32 vcc, 32, v173
	s_and_b64 s[2:3], s[4:5], s[2:3]
	s_and_b64 vcc, s[2:3], vcc
	v_cndmask_b32_e64 v95, v95, v130, s[64:65]
	v_cndmask_b32_e64 v94, v94, v130, s[62:63]
	v_cndmask_b32_e64 v93, v93, v130, s[60:61]
	v_cndmask_b32_e64 v92, v92, v130, s[58:59]
	v_cndmask_b32_e64 v91, v91, v130, s[56:57]
	v_cndmask_b32_e64 v90, v90, v130, s[54:55]
	v_cndmask_b32_e64 v89, v89, v130, s[52:53]
	v_cndmask_b32_e64 v88, v88, v130, s[50:51]
	v_cndmask_b32_e64 v87, v87, v130, s[48:49]
	v_cndmask_b32_e64 v86, v86, v130, s[46:47]
	v_cndmask_b32_e64 v85, v85, v130, s[44:45]
	v_cndmask_b32_e64 v84, v84, v130, s[42:43]
	v_cndmask_b32_e64 v83, v83, v130, s[40:41]
	v_cndmask_b32_e64 v82, v82, v130, s[38:39]
	v_cndmask_b32_e64 v81, v81, v130, s[36:37]
	v_cndmask_b32_e64 v79, v79, v130, s[34:35]
	v_cndmask_b32_e64 v78, v78, v130, s[28:29]
	v_cndmask_b32_e64 v77, v77, v130, s[26:27]
	v_cndmask_b32_e64 v76, v76, v130, s[24:25]
	v_cndmask_b32_e64 v75, v75, v130, s[22:23]
	v_cndmask_b32_e64 v74, v74, v130, s[20:21]
	v_cndmask_b32_e64 v73, v73, v130, s[18:19]
	v_cndmask_b32_e64 v72, v72, v130, s[16:17]
	v_cndmask_b32_e64 v71, v71, v130, s[14:15]
	v_cndmask_b32_e64 v70, v70, v130, s[12:13]
	v_cndmask_b32_e64 v69, v69, v130, s[10:11]
	v_cndmask_b32_e64 v68, v68, v130, s[8:9]
	v_cndmask_b32_e64 v67, v67, v130, s[6:7]
	v_cndmask_b32_e64 v66, v66, v130, s[4:5]
	v_cndmask_b32_e64 v65, v65, v130, s[2:3]
	v_cndmask_b32_e32 v64, v64, v130, vcc

; __device__ __forceinline__ void partialSM(f32x16& p0, f32x16& p1, float& m_reg, float& mn, float& alpha) {
;     float pmax = p0[0];
; #pragma unroll
;     for (int r = 1; r < 16; ++r) pmax = fmaxf(pmax, p0[r]);
; #pragma unroll
;     for (int r = 0; r < 16; ++r) pmax = fmaxf(pmax, p1[r]);
;     { auto rr = __builtin_amdgcn_permlane32_swap(__float_as_uint(pmax), __float_as_uint(pmax), false, false);
;       pmax = fmaxf(__uint_as_float(rr[0]), __uint_as_float(rr[1])); }
;     if (__builtin_expect(__all((pmax - m_reg) <= THR2), 1)) { mn = m_reg; alpha = 1.f; }
;     else { mn = fmaxf(m_reg, pmax); alpha = __builtin_amdgcn_exp2f(m_reg - mn); m_reg = mn; }
; #pragma unroll
;     for (int r = 0; r < 16; ++r) p0[r] = p0[r] - mn;
; #pragma unroll
;     for (int r = 0; r < 16; ++r) p1[r] = p1[r] - mn;
; #pragma unroll
;     for (int r = 0; r < 16; ++r) p0[r] = __builtin_amdgcn_exp2f(p0[r]);
; }
; __device__ __forceinline__ void finishSM(f32x16& p0, f32x16& p1, float alpha, float& l_reg, bf16x8& pa0, bf16x8& pa1, bf16x8& pa2, bf16x8& pa3) {
; #pragma unroll
;     for (int r = 0; r < 16; ++r) p1[r] = __builtin_amdgcn_exp2f(p1[r]);
;     float ps = 0;
; #pragma unroll
;     for (int r = 0; r < 16; ++r) ps += p0[r];
; #pragma unroll
;     for (int r = 0; r < 16; ++r) ps += p1[r];
;     { auto rr = __builtin_amdgcn_permlane32_swap(__float_as_uint(ps), __float_as_uint(ps), false, false);
;       ps = __uint_as_float(rr[0]) + __uint_as_float(rr[1]); }
;     l_reg = l_reg * alpha + ps;
;     ...
;     PK4(p0, 0, pa0); PK4(p0, 8, pa1); PK4(p1, 0, pa2); PK4(p1, 8, pa3);
;     ...
; }
; __device__ __forceinline__ void qkt(f32x16& p0, f32x16& p1, const char* Kslot, int r32, int hi, const bf16x8* qr, const LAS f32x4* cp) {
; #pragma unroll
;     for (int g = 0; g < 4; ++g) { const f32x4 c0 = cp[2 * g], c1 = cp[8 + 2 * g];
; #pragma unroll
;         for (int j = 0; j < 4; ++j) { p0[4 * g + j] = c0[j]; p1[4 * g + j] = c1[j]; } }
;     const char* kb[4];
; #pragma unroll
;     for (int dd = 0; dd < 4; ++dd) kb[dd] = Kslot + KSWZ(r32, (dd * 16 + hi * 8) * 2);
; #pragma unroll
;     for (int d0 = 0; d0 < 8; ++d0) { const char* a = kb[d0 & 3] + (d0 >> 2) * 128;
;         bf16x8 b0 = *reinterpret_cast<const bf16x8*>(a);
;         bf16x8 b1 = *reinterpret_cast<const bf16x8*>(a + 32 * 256);
;         p0 = __builtin_amdgcn_mfma_f32_32x32x16_bf16(b0, qr[d0], p0, 0, 0, 0);
.LBB0_572:
	v_cndmask_b32_e64 v144, v154, v144, s[2:3]
	v_sub_f32_e32 v80, v80, v144
	v_sub_f32_e32 v81, v81, v144
	v_sub_f32_e32 v82, v82, v144
	v_sub_f32_e32 v83, v83, v144
	v_sub_f32_e32 v84, v84, v144
	v_sub_f32_e32 v85, v85, v144
	v_sub_f32_e32 v86, v86, v144
	v_sub_f32_e32 v87, v87, v144
	v_sub_f32_e32 v88, v88, v144
	v_sub_f32_e32 v89, v89, v144
	v_sub_f32_e32 v90, v90, v144
	v_sub_f32_e32 v91, v91, v144
	v_sub_f32_e32 v92, v92, v144
	v_sub_f32_e32 v93, v93, v144
	v_sub_f32_e32 v94, v94, v144
	v_sub_f32_e32 v95, v95, v144
	v_sub_f32_e32 v154, v64, v144
	v_sub_f32_e32 v155, v65, v144
	v_sub_f32_e32 v156, v66, v144
	v_sub_f32_e32 v157, v67, v144
	v_sub_f32_e32 v158, v68, v144
	v_sub_f32_e32 v159, v69, v144
	v_sub_f32_e32 v160, v70, v144
	v_sub_f32_e32 v161, v71, v144
	v_sub_f32_e32 v162, v72, v144
	v_sub_f32_e32 v163, v73, v144
	v_sub_f32_e32 v164, v74, v144
	v_sub_f32_e32 v165, v75, v144
	v_sub_f32_e32 v166, v76, v144
	v_exp_f32_e32 v167, v80
	v_exp_f32_e32 v168, v81
	v_exp_f32_e32 v169, v82
	v_exp_f32_e32 v178, v83
	v_exp_f32_e32 v179, v84
	v_exp_f32_e32 v198, v85
	v_exp_f32_e32 v199, v86
	v_exp_f32_e32 v200, v87
	v_exp_f32_e32 v201, v88
	v_exp_f32_e32 v202, v89
	v_exp_f32_e32 v203, v90
	v_exp_f32_e32 v204, v91
	v_exp_f32_e32 v205, v92
	v_exp_f32_e32 v206, v93
	v_exp_f32_e32 v207, v94
	v_exp_f32_e32 v208, v95
	v_sub_f32_e32 v209, v77, v144
	v_sub_f32_e32 v210, v78, v144
	v_sub_f32_e32 v211, v79, v144
	s_add_i32 s2, s90, 0
	v_add_u32_e32 v212, s2, v193
	ds_read_b128 v[80:83], v197 offset:256
	ds_read_b128 v[84:87], v197 offset:288
	ds_read_b128 v[64:67], v197 offset:384
	ds_read_b128 v[68:71], v197 offset:416
	ds_read_b128 v[88:91], v197 offset:320
	ds_read_b128 v[72:75], v197 offset:448
	ds_read_b128 v[92:95], v197 offset:352
	ds_read_b128 v[76:79], v197 offset:480
	ds_read_b128 v[146:149], v212 offset:49152
	ds_read_b128 v[150:153], v212 offset:57344
	v_add_u32_e32 v213, s2, v194
	v_add_u32_e32 v214, s2, v195
	s_waitcnt lgkmcnt(0)
	v_mfma_f32_32x32x16_bf16 v[80:95], v[146:149], v[96:99], v[80:95]
	v_add_u32_e32 v215, s2, v196
	v_exp_f32_e32 v157, v157
	v_exp_f32_e32 v158, v158
	v_exp_f32_e32 v159, v159
	v_exp_f32_e32 v160, v160
	v_exp_f32_e32 v161, v161
	v_exp_f32_e32 v162, v162
	v_mfma_f32_32x32x16_bf16 v[64:79], v[150:153], v[96:99], v[64:79]
	ds_read_b128 v[146:149], v213 offset:49152
	ds_read_b128 v[150:153], v213 offset:57344
	v_exp_f32_e32 v163, v163
	v_exp_f32_e32 v164, v164
	v_exp_f32_e32 v165, v165
	v_exp_f32_e32 v166, v166
	v_exp_f32_e32 v209, v209
	v_exp_f32_e32 v210, v210
	s_waitcnt lgkmcnt(0)
	v_mfma_f32_32x32x16_bf16 v[80:95], v[146:149], v[100:103], v[80:95]
	v_exp_f32_e32 v211, v211
	v_mfma_f32_32x32x16_bf16 v[64:79], v[150:153], v[100:103], v[64:79]
	ds_read_b128 v[146:149], v214 offset:49152
	ds_read_b128 v[150:153], v214 offset:57344
	s_waitcnt lgkmcnt(0)
	v_mfma_f32_32x32x16_bf16 v[80:95], v[146:149], v[104:107], v[80:95]
	v_mfma_f32_32x32x16_bf16 v[64:79], v[150:153], v[104:107], v[64:79]
	ds_read_b128 v[146:149], v215 offset:49152
	ds_read_b128 v[150:153], v215 offset:57344
	s_waitcnt lgkmcnt(0)
	v_mfma_f32_32x32x16_bf16 v[80:95], v[146:149], v[108:111], v[80:95]
	v_mfma_f32_32x32x16_bf16 v[64:79], v[150:153], v[108:111], v[64:79]
	v_xor_b32_e32 v249, 0x80, v212
	v_xor_b32_e32 v250, 0x80, v213
	v_xor_b32_e32 v251, 0x80, v214
	v_xor_b32_e32 v252, 0x80, v215
	ds_read_b128 v[146:149], v249 offset:49152
	ds_read_b128 v[150:153], v249 offset:57344
	v_exp_f32_e32 v212, v154
	s_waitcnt lgkmcnt(0)
	v_mfma_f32_32x32x16_bf16 v[80:95], v[146:149], v[112:115], v[80:95]
	v_mfma_f32_32x32x16_bf16 v[64:79], v[150:153], v[112:115], v[64:79]
	ds_read_b128 v[146:149], v250 offset:49152
	ds_read_b128 v[150:153], v250 offset:57344
	v_exp_f32_e32 v213, v155
	s_waitcnt lgkmcnt(0)
	v_mfma_f32_32x32x16_bf16 v[80:95], v[146:149], v[116:119], v[80:95]
	v_mfma_f32_32x32x16_bf16 v[64:79], v[150:153], v[116:119], v[64:79]
	ds_read_b128 v[146:149], v251 offset:49152
	ds_read_b128 v[150:153], v251 offset:57344
	v_exp_f32_e32 v214, v156
	s_waitcnt lgkmcnt(0)
	v_mfma_f32_32x32x16_bf16 v[80:95], v[146:149], v[120:123], v[80:95]
	v_mfma_f32_32x32x16_bf16 v[64:79], v[150:153], v[120:123], v[64:79]
	ds_read_b128 v[146:149], v252 offset:49152
	ds_read_b128 v[150:153], v252 offset:57344
	s_waitcnt lgkmcnt(0)
	v_mfma_f32_32x32x16_bf16 v[80:95], v[146:149], v[124:127], v[80:95]
	v_add_f32_e32 v146, 0, v167
	v_add_f32_e32 v146, v168, v146
	v_add_f32_e32 v146, v169, v146
	v_add_f32_e32 v146, v178, v146
	v_add_f32_e32 v146, v179, v146
	v_add_f32_e32 v146, v198, v146
	v_add_f32_e32 v146, v199, v146
	v_add_f32_e32 v146, v200, v146
	v_add_f32_e32 v146, v201, v146
	v_add_f32_e32 v146, v202, v146
	v_add_f32_e32 v146, v203, v146
	v_add_f32_e32 v146, v204, v146
	v_add_f32_e32 v146, v205, v146
	v_add_f32_e32 v146, v206, v146
	v_add_f32_e32 v146, v207, v146
	v_add_f32_e32 v146, v208, v146
	v_add_f32_e32 v146, v212, v146
	v_add_f32_e32 v146, v213, v146
	v_add_f32_e32 v146, v214, v146
	v_add_f32_e32 v146, v157, v146
	v_add_f32_e32 v146, v158, v146
	v_add_f32_e32 v146, v159, v146
	v_add_f32_e32 v146, v160, v146
	v_add_f32_e32 v146, v161, v146
	v_add_f32_e32 v146, v162, v146
	v_add_f32_e32 v146, v163, v146
	v_mfma_f32_32x32x16_bf16 v[64:79], v[150:153], v[124:127], v[64:79]
	v_add_f32_e32 v146, v164, v146
	v_add_f32_e32 v146, v165, v146
	v_add_f32_e32 v146, v166, v146
	v_add_f32_e32 v146, v209, v146
	v_add_f32_e32 v146, v210, v146
	v_add_f32_e32 v146, v211, v146
	v_mov_b32_e32 v147, v146
	s_nop 1
	v_permlane32_swap_b32_e32 v146, v147
	v_cvt_pk_bf16_f32 v148, v167, v168
	v_cvt_pk_bf16_f32 v149, v169, v178
	v_cvt_pk_bf16_f32 v150, v179, v198
	v_cvt_pk_bf16_f32 v151, v199, v200
	v_cvt_pk_bf16_f32 v152, v201, v202
	v_cvt_pk_bf16_f32 v153, v203, v204
	v_cvt_pk_bf16_f32 v154, v205, v206
	v_cvt_pk_bf16_f32 v155, v207, v208
	v_cvt_pk_bf16_f32 v156, v212, v213
	v_cvt_pk_bf16_f32 v157, v214, v157
	v_cvt_pk_bf16_f32 v158, v158, v159
	v_cvt_pk_bf16_f32 v159, v160, v161
	v_cvt_pk_bf16_f32 v160, v162, v163
	v_cvt_pk_bf16_f32 v161, v164, v165
	v_cvt_pk_bf16_f32 v162, v166, v209
	v_cvt_pk_bf16_f32 v163, v210, v211
	s_nop 0
	v_permlane32_swap_b32_e32 v148, v150
	v_permlane32_swap_b32_e32 v149, v151
	v_permlane32_swap_b32_e32 v152, v154
	v_permlane32_swap_b32_e32 v153, v155
	v_permlane32_swap_b32_e32 v156, v158
	v_permlane32_swap_b32_e32 v157, v159
	v_permlane32_swap_b32_e32 v160, v162
	v_permlane32_swap_b32_e32 v161, v163
	v_add_u32_e32 v168, s73, v192
	ds_read_b64_tr_b16 v[164:165], v168 offset:0
	ds_read_b64_tr_b16 v[166:167], v168 offset:0x800
	ds_read_b64_tr_b16 v[198:199], v168 offset:0x1000
	ds_read_b64_tr_b16 v[200:201], v168 offset:0x1800
	ds_read_b64_tr_b16 v[202:203], v168 offset:0x2000
	ds_read_b64_tr_b16 v[204:205], v168 offset:0x2800
	ds_read_b64_tr_b16 v[206:207], v168 offset:0x3000
	ds_read_b64_tr_b16 v[208:209], v168 offset:0x3800
	s_waitcnt lgkmcnt(4)
; #define SBAR() __builtin_amdgcn_sched_barrier(0)
; #define PV_RD(d0, kh, X) do { constexpr int b_ = v_rd_off(d0, 2 * (kh), 0); TRRD(X##l0, b_); TRRD(X##h0, b_ + 2048); TRRD(X##l1, b_ + 4096); TRRD(X##h1, b_ + 6144); } while (0)
; #define PV_MM(d0, X, PA, PB) do { \
;         o[d0] = __builtin_amdgcn_mfma_f32_32x32x16_bf16(PA, (bf16x8){X##l0[0], X##l0[1], X##l0[2], X##l0[3], X##h0[0], X##h0[1], X##h0[2], X##h0[3]}, o[d0], 0, 0, 0);   \
;         o[d0] = __builtin_amdgcn_mfma_f32_32x32x16_bf16(PB, (bf16x8){X##l1[0], X##l1[1], X##l1[2], X##l1[3], X##h1[0], X##h1[1], X##h1[2], X##h1[3]}, o[d0], 0, 0, 0); } while (0)
; #define PV_W4() do { asm volatile("s_waitcnt lgkmcnt(4)" ::: "memory"); SBAR(); } while (0)
; #define PV_W0() do { asm volatile("s_waitcnt lgkmcnt(0)" ::: "memory"); SBAR(); } while (0)
; __device__ __forceinline__ void mask_tile(f32x16& p0, f32x16& p1, int dq) {
;     const float NEG = -__builtin_inff();
; #pragma unroll
;     for (int r = 0; r < 16; ++r) { const int c = (r & 3) + 8 * (r >> 2); if (dq - c < 0) p0[r] = NEG; if (dq - c - 32 < 0) p1[r] = NEG; }
; }
; __device__ __forceinline__ void pv_tile(f32x16* o, int vb0, bf16x8 pa0, bf16x8 pa1, bf16x8 pa2, bf16x8 pa3) {
;     ...
;     s16x4 al0, al1, ah0, ah1, bl0, bl1, bh0, bh1;
;     PV_RD(0, 0, a);
;     PV_RD(0, 1, b); PV_W4(); PV_MM(0, a, pa0, pa1); SBAR();
;     PV_RD(1, 0, a); PV_W4(); PV_MM(0, b, pa2, pa3); SBAR();
;     PV_RD(1, 1, b); PV_W4(); PV_MM(1, a, pa0, pa1); SBAR();
;     PV_RD(2, 0, a); PV_W4(); PV_MM(1, b, pa2, pa3); SBAR();
;     PV_RD(2, 1, b); PV_W4(); PV_MM(2, a, pa0, pa1); SBAR();
;     PV_RD(3, 0, a); PV_W4(); PV_MM(2, b, pa2, pa3); SBAR();
;     PV_RD(3, 1, b); PV_W4(); PV_MM(3, a, pa0, pa1); SBAR();
;     PV_W0(); PV_MM(3, b, pa2, pa3);
	s_nop 0
	v_mfma_f32_32x32x16_bf16 v[48:63], v[148:151], v[164:167], v[48:63]
	v_mfma_f32_32x32x16_bf16 v[48:63], v[152:155], v[198:201], v[48:63]
	ds_read_b64_tr_b16 v[164:165], v168 offset:0x200
	ds_read_b64_tr_b16 v[166:167], v168 offset:0xa00
	ds_read_b64_tr_b16 v[198:199], v168 offset:0x1200
	ds_read_b64_tr_b16 v[200:201], v168 offset:0x1a00
	s_waitcnt lgkmcnt(4)
	v_mfma_f32_32x32x16_bf16 v[48:63], v[156:159], v[202:205], v[48:63]
	v_mfma_f32_32x32x16_bf16 v[48:63], v[160:163], v[206:209], v[48:63]
	ds_read_b64_tr_b16 v[202:203], v168 offset:0x2200
	ds_read_b64_tr_b16 v[204:205], v168 offset:0x2a00
	ds_read_b64_tr_b16 v[206:207], v168 offset:0x3200
	ds_read_b64_tr_b16 v[208:209], v168 offset:0x3a00
	s_waitcnt lgkmcnt(4)
	v_mfma_f32_32x32x16_bf16 v[32:47], v[148:151], v[164:167], v[32:47]
	v_mfma_f32_32x32x16_bf16 v[32:47], v[152:155], v[198:201], v[32:47]
	ds_read_b64_tr_b16 v[164:165], v168 offset:0x400
	ds_read_b64_tr_b16 v[166:167], v168 offset:0xc00
	ds_read_b64_tr_b16 v[198:199], v168 offset:0x1400
	ds_read_b64_tr_b16 v[200:201], v168 offset:0x1c00
	s_waitcnt lgkmcnt(4)
	v_mfma_f32_32x32x16_bf16 v[32:47], v[156:159], v[202:205], v[32:47]
	v_mfma_f32_32x32x16_bf16 v[32:47], v[160:163], v[206:209], v[32:47]
	ds_read_b64_tr_b16 v[202:203], v168 offset:0x2400
	ds_read_b64_tr_b16 v[204:205], v168 offset:0x2c00
	ds_read_b64_tr_b16 v[206:207], v168 offset:0x3400
	ds_read_b64_tr_b16 v[208:209], v168 offset:0x3c00
	s_waitcnt lgkmcnt(4)
	v_mfma_f32_32x32x16_bf16 v[16:31], v[148:151], v[164:167], v[16:31]
	v_mfma_f32_32x32x16_bf16 v[16:31], v[152:155], v[198:201], v[16:31]
	ds_read_b64_tr_b16 v[164:165], v168 offset:0x600
	ds_read_b64_tr_b16 v[166:167], v168 offset:0xe00
	ds_read_b64_tr_b16 v[198:199], v168 offset:0x1600
	ds_read_b64_tr_b16 v[200:201], v168 offset:0x1e00
	s_waitcnt lgkmcnt(4)
	v_mfma_f32_32x32x16_bf16 v[16:31], v[156:159], v[202:205], v[16:31]
	v_mfma_f32_32x32x16_bf16 v[16:31], v[160:163], v[206:209], v[16:31]
	ds_read_b64_tr_b16 v[202:203], v168 offset:0x2600
	ds_read_b64_tr_b16 v[204:205], v168 offset:0x2e00
	ds_read_b64_tr_b16 v[206:207], v168 offset:0x3600
	ds_read_b64_tr_b16 v[208:209], v168 offset:0x3e00
	s_waitcnt lgkmcnt(4)
	v_mfma_f32_32x32x16_bf16 v[0:15], v[148:151], v[164:167], v[0:15]
	v_mfma_f32_32x32x16_bf16 v[0:15], v[152:155], v[198:201], v[0:15]
	s_waitcnt lgkmcnt(0)
	v_mfma_f32_32x32x16_bf16 v[0:15], v[156:159], v[202:205], v[0:15]
	s_cmp_le_i32 s91, s88
	v_mfma_f32_32x32x16_bf16 v[0:15], v[160:163], v[206:209], v[0:15]
	s_cbranch_scc1 .LBB0_574
	v_subrev_u32_e32 v148, 64, v173
	v_cmp_gt_i32_e64 s[62:63], 26, v148
	v_cmp_gt_i32_e64 s[64:65], 27, v148
	v_cmp_gt_i32_e64 s[60:61], 25, v148
	s_and_b64 s[62:63], s[64:65], s[62:63]
	v_cmp_gt_i32_e64 s[58:59], 24, v148
	s_and_b64 s[60:61], s[62:63], s[60:61]
	v_cmp_gt_i32_e64 s[56:57], 19, v148
	s_and_b64 s[58:59], s[60:61], s[58:59]
	v_cmp_gt_i32_e64 s[54:55], 18, v148
	s_and_b64 s[56:57], s[58:59], s[56:57]
	v_cmp_gt_i32_e64 s[52:53], 17, v148
	s_and_b64 s[54:55], s[56:57], s[54:55]
	v_cmp_gt_i32_e64 s[50:51], 16, v148
	s_and_b64 s[52:53], s[54:55], s[52:53]
	v_cmp_gt_i32_e64 s[48:49], 11, v148
	s_and_b64 s[50:51], s[52:53], s[50:51]
	v_cmp_gt_i32_e64 s[46:47], 10, v148
	s_and_b64 s[48:49], s[50:51], s[48:49]
	v_cmp_gt_i32_e64 s[44:45], 9, v148
	s_and_b64 s[46:47], s[48:49], s[46:47]
	v_cmp_gt_i32_e64 s[42:43], 8, v148
	s_and_b64 s[44:45], s[46:47], s[44:45]
	v_cmp_gt_i32_e64 s[40:41], 3, v148
	s_and_b64 s[42:43], s[44:45], s[42:43]
	v_cmp_gt_i32_e64 s[38:39], 2, v148
	s_and_b64 s[40:41], s[42:43], s[40:41]
	v_cmp_gt_i32_e64 s[36:37], 1, v148
	s_and_b64 s[38:39], s[40:41], s[38:39]
	v_cmp_gt_i32_e64 s[34:35], 0, v148
	s_and_b64 s[36:37], s[38:39], s[36:37]
	s_and_b64 s[34:35], s[36:37], s[34:35]
	v_cmp_gt_i32_e64 s[28:29], 58, v148
	v_cndmask_b32_e64 v80, v80, v130, s[34:35]
	v_cmp_gt_i32_e64 s[34:35], 59, v148
	v_cmp_gt_i32_e64 s[26:27], 57, v148
	s_and_b64 s[28:29], s[34:35], s[28:29]
	v_cmp_gt_i32_e64 s[24:25], 56, v148
	s_and_b64 s[26:27], s[28:29], s[26:27]
	v_cmp_gt_i32_e64 s[22:23], 51, v148
	s_and_b64 s[24:25], s[26:27], s[24:25]
	v_cmp_gt_i32_e64 s[20:21], 50, v148
	s_and_b64 s[22:23], s[24:25], s[22:23]
	v_cmp_gt_i32_e64 s[18:19], 49, v148
	s_and_b64 s[20:21], s[22:23], s[20:21]
	v_cmp_gt_i32_e64 s[16:17], 48, v148
	s_and_b64 s[18:19], s[20:21], s[18:19]
	v_cmp_gt_i32_e64 s[14:15], 43, v148
	s_and_b64 s[16:17], s[18:19], s[16:17]
	v_cmp_gt_i32_e64 s[12:13], 42, v148
	s_and_b64 s[14:15], s[16:17], s[14:15]
	v_cmp_gt_i32_e64 s[10:11], 41, v148
	s_and_b64 s[12:13], s[14:15], s[12:13]
	v_cmp_gt_i32_e64 s[8:9], 40, v148
	s_and_b64 s[10:11], s[12:13], s[10:11]
	v_cmp_gt_i32_e64 s[6:7], 35, v148
	s_and_b64 s[8:9], s[10:11], s[8:9]
	v_cmp_gt_i32_e64 s[4:5], 34, v148
	s_and_b64 s[6:7], s[8:9], s[6:7]
	v_cmp_gt_i32_e64 s[2:3], 33, v148
	s_and_b64 s[4:5], s[6:7], s[4:5]
	v_cmp_gt_i32_e32 vcc, 32, v148
	s_and_b64 s[2:3], s[4:5], s[2:3]
	s_and_b64 vcc, s[2:3], vcc
	v_cndmask_b32_e64 v95, v95, v130, s[64:65]
	v_cndmask_b32_e64 v94, v94, v130, s[62:63]
	v_cndmask_b32_e64 v93, v93, v130, s[60:61]
	v_cndmask_b32_e64 v92, v92, v130, s[58:59]
	v_cndmask_b32_e64 v91, v91, v130, s[56:57]
	v_cndmask_b32_e64 v90, v90, v130, s[54:55]
	v_cndmask_b32_e64 v89, v89, v130, s[52:53]
	v_cndmask_b32_e64 v88, v88, v130, s[50:51]
	v_cndmask_b32_e64 v87, v87, v130, s[48:49]
	v_cndmask_b32_e64 v86, v86, v130, s[46:47]
	v_cndmask_b32_e64 v85, v85, v130, s[44:45]
	v_cndmask_b32_e64 v84, v84, v130, s[42:43]
	v_cndmask_b32_e64 v83, v83, v130, s[40:41]
	v_cndmask_b32_e64 v82, v82, v130, s[38:39]
	v_cndmask_b32_e64 v81, v81, v130, s[36:37]
	v_cndmask_b32_e64 v79, v79, v130, s[34:35]
	v_cndmask_b32_e64 v78, v78, v130, s[28:29]
	v_cndmask_b32_e64 v77, v77, v130, s[26:27]
	v_cndmask_b32_e64 v76, v76, v130, s[24:25]
	v_cndmask_b32_e64 v75, v75, v130, s[22:23]
	v_cndmask_b32_e64 v74, v74, v130, s[20:21]
	v_cndmask_b32_e64 v73, v73, v130, s[18:19]
	v_cndmask_b32_e64 v72, v72, v130, s[16:17]
	v_cndmask_b32_e64 v71, v71, v130, s[14:15]
	v_cndmask_b32_e64 v70, v70, v130, s[12:13]
	v_cndmask_b32_e64 v69, v69, v130, s[10:11]
	v_cndmask_b32_e64 v68, v68, v130, s[8:9]
	v_cndmask_b32_e64 v67, v67, v130, s[6:7]
	v_cndmask_b32_e64 v66, v66, v130, s[4:5]
	v_cndmask_b32_e64 v65, v65, v130, s[2:3]
	v_cndmask_b32_e32 v64, v64, v130, vcc
